# pass-C FFT loops: twiddle (loop-invariant) read and its derived factors computed once for both unrolled sub-iterations
# baseline (speedup 1.0000x reference)
; #define LAS __attribute__((address_space(3)))
; __device__ __forceinline__ cf twc(cf ws, int k16) { if (k16 == 0) return ws; if (k16 == 4) return cf{ws.y, -ws.x}; return cmul(ws, cf{c16(k16), -s16(k16)}); }
; template <int LR> __device__ __forceinline__ void dif_reg(cf (&x)[1 << LR], cf w) {
;     constexpr int R = 1 << LR; cf ws = w;
; #pragma unroll
;     for (int s = 0; s < LR; ++s) { const int half = R >> (s + 1);
; #pragma unroll
;         for (int m0 = 0; m0 < R; m0 += 2 * half)
; #pragma unroll
;             for (int mm = 0; mm < half; ++mm) { const int ia = m0 + mm, ib = ia + half; const cf a = x[ia], b = x[ib];
;                 x[ia] = cf{a.x + b.x, a.y + b.y}; const cf d{a.x - b.x, a.y - b.y};
;                 x[ib] = cmul(d, twc(ws, (mm << s) * (16 / R))); }
;         ws = cmul(ws, ws); }
; }
; template <int LR> __device__ __forceinline__ void dit_reg(cf (&x)[1 << LR], cf w) {
;     constexpr int R = 1 << LR; cf wsv[LR]; wsv[0] = w;
; #pragma unroll
;     for (int s = 1; s < LR; ++s) wsv[s] = cmul(wsv[s - 1], wsv[s - 1]);
; #pragma unroll
;     for (int s = LR - 1; s >= 0; --s) { const int half = R >> (s + 1);
; #pragma unroll
;         for (int m0 = 0; m0 < R; m0 += 2 * half)
; #pragma unroll
;             for (int mm = 0; mm < half; ++mm) { const int ia = m0 + mm, ib = ia + half; const cf a = x[ia];
;                 const cf b = cmulc(x[ib], twc(wsv[s], (mm << s) * (16 / R)));
;                 x[ia] = cf{a.x + b.x, a.y + b.y}; x[ib] = cf{a.x - b.x, a.y - b.y}; } }
; }
; __device__ __forceinline__ void lds_barrier() { asm volatile("s_waitcnt lgkmcnt(0)\n\ts_barrier" ::: "memory"); }
; template <int LR, bool INV> __device__ __forceinline__ void fft_pass(ldsf2 buf, int base, int stride, int twi) {
;     constexpr int R = 1 << LR; cf x[R];
;     const v2f wv = ((ldsf2)((LAS unsigned char*)buf + 139264))[twi];
; #pragma unroll
;     for (int m = 0; m < R; ++m) { const v2f v = buf[base + m * stride]; x[m] = cf{v.x, v.y}; }
;     const cf w{wv.x, wv.y};
;     if (INV) dit_reg<LR>(x, w); else dif_reg<LR>(x, w);
; #pragma unroll
;     for (int m = 0; m < R; ++m) buf[base + m * stride] = mkv2(x[m].x, x[m].y);
; }
.LBB0_351:
	v_or_b32_e32 v73, s0, v69
	ds_read_b64 v[90:91], v72
	v_lshlrev_b32_e32 v74, 3, v73
	v_ashrrev_i32_e32 v73, 1, v73
	v_add3_u32 v73, v68, v74, v73
	ds_read2_b64 v[74:77], v73 offset1:17
	ds_read2_b64 v[78:81], v73 offset0:34 offset1:51
	ds_read2_b64 v[82:85], v73 offset0:68 offset1:85
	ds_read2_b64 v[86:89], v73 offset0:102 offset1:119
	s_movk_i32 s0, 0x200
	v_or_b32_e32 v118, s0, v69
	v_lshlrev_b32_e32 v122, 3, v118
	v_ashrrev_i32_e32 v118, 1, v118
	v_add3_u32 v118, v68, v122, v118
	ds_read2_b64 v[124:127], v118 offset1:17
	ds_read2_b64 v[128:131], v118 offset0:34 offset1:51
	ds_read2_b64 v[132:135], v118 offset0:68 offset1:85
	ds_read2_b64 v[148:151], v118 offset0:102 offset1:119
	s_waitcnt lgkmcnt(4)
	v_pk_add_f32 v[92:93], v[90:91], v[90:91] op_sel:[0,1] op_sel_hi:[1,0] neg_lo:[0,0] neg_hi:[0,1]
	v_pk_mul_f32 v[98:99], v[90:91], v[90:91] op_sel:[1,1] op_sel_hi:[1,0]
	v_pk_mul_f32 v[94:95], v[92:93], s[16:17] op_sel:[0,0] op_sel_hi:[1,0]
	v_pk_fma_f32 v[98:99], v[90:91], v[90:91], v[98:99] op_sel:[0,0,0] op_sel_hi:[0,1,1] neg_lo:[0,0,1] neg_hi:[0,0,0]
	v_pk_mul_f32 v[96:97], v[92:93], s[16:17] op_sel:[1,0] op_sel_hi:[0,0] neg_lo:[0,0] neg_hi:[1,0]
	s_nop 0
	v_pk_mul_f32 v[100:101], v[98:99], v[98:99] op_sel:[1,1] op_sel_hi:[1,0]
	s_nop 0
	v_pk_fma_f32 v[100:101], v[98:99], v[98:99], v[100:101] op_sel:[0,0,0] op_sel_hi:[0,1,1] neg_lo:[0,0,1] neg_hi:[0,0,0]
	v_pk_add_f32 v[102:103], v[74:75], v[82:83] neg_lo:[0,1] neg_hi:[0,1]
	v_pk_add_f32 v[104:105], v[76:77], v[84:85] neg_lo:[0,1] neg_hi:[0,1]
	v_pk_add_f32 v[106:107], v[78:79], v[86:87] neg_lo:[0,1] neg_hi:[0,1]
	v_pk_add_f32 v[108:109], v[80:81], v[88:89] neg_lo:[0,1] neg_hi:[0,1]
	v_pk_add_f32 v[74:75], v[74:75], v[82:83]
	v_pk_add_f32 v[76:77], v[76:77], v[84:85]
	v_pk_add_f32 v[78:79], v[78:79], v[86:87]
	v_pk_add_f32 v[80:81], v[80:81], v[88:89]
	v_pk_mul_f32 v[82:83], v[102:103], v[90:91] op_sel:[1,1] op_sel_hi:[1,0]
	v_pk_mul_f32 v[84:85], v[104:105], v[94:95] op_sel:[1,1] op_sel_hi:[1,0]
	v_pk_mul_f32 v[86:87], v[106:107], v[90:91] op_sel:[1,0] op_sel_hi:[1,1]
	v_pk_mul_f32 v[88:89], v[108:109], v[96:97] op_sel:[1,1] op_sel_hi:[1,0]
	v_pk_fma_f32 v[82:83], v[102:103], v[90:91], v[82:83] op_sel:[0,0,0] op_sel_hi:[0,1,1] neg_lo:[0,0,1] neg_hi:[0,0,0]
	v_pk_fma_f32 v[84:85], v[104:105], v[94:95], v[84:85] op_sel:[0,0,0] op_sel_hi:[0,1,1] neg_lo:[0,0,1] neg_hi:[0,0,0]
	v_pk_fma_f32 v[86:87], v[106:107], v[90:91], v[86:87] op_sel:[0,1,0] op_sel_hi:[0,0,1] neg_lo:[0,0,0] neg_hi:[0,1,0]
	v_pk_fma_f32 v[88:89], v[108:109], v[96:97], v[88:89] op_sel:[0,0,0] op_sel_hi:[0,1,1] neg_lo:[0,0,1] neg_hi:[0,0,0]
	v_pk_add_f32 v[102:103], v[74:75], v[78:79] neg_lo:[0,1] neg_hi:[0,1]
	v_pk_add_f32 v[104:105], v[76:77], v[80:81] neg_lo:[0,1] neg_hi:[0,1]
	v_pk_add_f32 v[106:107], v[82:83], v[86:87] neg_lo:[0,1] neg_hi:[0,1]
	v_pk_add_f32 v[108:109], v[84:85], v[88:89] neg_lo:[0,1] neg_hi:[0,1]
	v_pk_add_f32 v[74:75], v[74:75], v[78:79]
	v_pk_add_f32 v[76:77], v[76:77], v[80:81]
	v_pk_add_f32 v[82:83], v[82:83], v[86:87]
	v_pk_add_f32 v[84:85], v[84:85], v[88:89]
	v_pk_mul_f32 v[78:79], v[102:103], v[98:99] op_sel:[1,1] op_sel_hi:[1,0]
	v_pk_mul_f32 v[80:81], v[104:105], v[98:99] op_sel:[1,0] op_sel_hi:[1,1]
	v_pk_mul_f32 v[86:87], v[106:107], v[98:99] op_sel:[1,1] op_sel_hi:[1,0]
	v_pk_mul_f32 v[88:89], v[108:109], v[98:99] op_sel:[1,0] op_sel_hi:[1,1]
	v_pk_fma_f32 v[78:79], v[102:103], v[98:99], v[78:79] op_sel:[0,0,0] op_sel_hi:[0,1,1] neg_lo:[0,0,1] neg_hi:[0,0,0]
	v_pk_fma_f32 v[80:81], v[104:105], v[98:99], v[80:81] op_sel:[0,1,0] op_sel_hi:[0,0,1] neg_lo:[0,0,0] neg_hi:[0,1,0]
	v_pk_fma_f32 v[86:87], v[106:107], v[98:99], v[86:87] op_sel:[0,0,0] op_sel_hi:[0,1,1] neg_lo:[0,0,1] neg_hi:[0,0,0]
	v_pk_fma_f32 v[88:89], v[108:109], v[98:99], v[88:89] op_sel:[0,1,0] op_sel_hi:[0,0,1] neg_lo:[0,0,0] neg_hi:[0,1,0]
	v_pk_add_f32 v[102:103], v[74:75], v[76:77] neg_lo:[0,1] neg_hi:[0,1]
	v_pk_add_f32 v[104:105], v[78:79], v[80:81] neg_lo:[0,1] neg_hi:[0,1]
	v_pk_add_f32 v[106:107], v[82:83], v[84:85] neg_lo:[0,1] neg_hi:[0,1]
	v_pk_add_f32 v[108:109], v[86:87], v[88:89] neg_lo:[0,1] neg_hi:[0,1]
	v_pk_add_f32 v[74:75], v[74:75], v[76:77]
	v_pk_add_f32 v[78:79], v[78:79], v[80:81]
	v_pk_add_f32 v[82:83], v[82:83], v[84:85]
	v_pk_add_f32 v[86:87], v[86:87], v[88:89]
	v_pk_mul_f32 v[76:77], v[102:103], v[100:101] op_sel:[1,1] op_sel_hi:[1,0]
	v_pk_mul_f32 v[80:81], v[104:105], v[100:101] op_sel:[1,1] op_sel_hi:[1,0]
	v_pk_mul_f32 v[84:85], v[106:107], v[100:101] op_sel:[1,1] op_sel_hi:[1,0]
	v_pk_mul_f32 v[88:89], v[108:109], v[100:101] op_sel:[1,1] op_sel_hi:[1,0]
	v_pk_fma_f32 v[76:77], v[102:103], v[100:101], v[76:77] op_sel:[0,0,0] op_sel_hi:[0,1,1] neg_lo:[0,0,1] neg_hi:[0,0,0]
	v_pk_fma_f32 v[80:81], v[104:105], v[100:101], v[80:81] op_sel:[0,0,0] op_sel_hi:[0,1,1] neg_lo:[0,0,1] neg_hi:[0,0,0]
	v_pk_fma_f32 v[84:85], v[106:107], v[100:101], v[84:85] op_sel:[0,0,0] op_sel_hi:[0,1,1] neg_lo:[0,0,1] neg_hi:[0,0,0]
	v_pk_fma_f32 v[88:89], v[108:109], v[100:101], v[88:89] op_sel:[0,0,0] op_sel_hi:[0,1,1] neg_lo:[0,0,1] neg_hi:[0,0,0]
	ds_write2_b64 v73, v[74:75], v[76:77] offset1:17
	ds_write2_b64 v73, v[78:79], v[80:81] offset0:34 offset1:51
	ds_write2_b64 v73, v[82:83], v[84:85] offset0:68 offset1:85
	ds_write2_b64 v73, v[86:87], v[88:89] offset0:102 offset1:119
	s_waitcnt lgkmcnt(4)
; #define LAS __attribute__((address_space(3)))
; template <int LR> __device__ __forceinline__ void dif_reg(cf (&x)[1 << LR], cf w) {
;     constexpr int R = 1 << LR; cf ws = w;
; #pragma unroll
;     for (int s = 0; s < LR; ++s) { const int half = R >> (s + 1);
; #pragma unroll
;         for (int m0 = 0; m0 < R; m0 += 2 * half)
; #pragma unroll
;             for (int mm = 0; mm < half; ++mm) { const int ia = m0 + mm, ib = ia + half; const cf a = x[ia], b = x[ib];
;                 x[ia] = cf{a.x + b.x, a.y + b.y}; const cf d{a.x - b.x, a.y - b.y};
;                 x[ib] = cmul(d, twc(ws, (mm << s) * (16 / R))); }
;         ws = cmul(ws, ws); }
; }
; template <int LR> __device__ __forceinline__ void dit_reg(cf (&x)[1 << LR], cf w) {
;     constexpr int R = 1 << LR; cf wsv[LR]; wsv[0] = w;
; #pragma unroll
;     for (int s = 1; s < LR; ++s) wsv[s] = cmul(wsv[s - 1], wsv[s - 1]);
; #pragma unroll
;     for (int s = LR - 1; s >= 0; --s) { const int half = R >> (s + 1);
; #pragma unroll
;         for (int m0 = 0; m0 < R; m0 += 2 * half)
; #pragma unroll
;             for (int mm = 0; mm < half; ++mm) { const int ia = m0 + mm, ib = ia + half; const cf a = x[ia];
;                 const cf b = cmulc(x[ib], twc(wsv[s], (mm << s) * (16 / R)));
;                 x[ia] = cf{a.x + b.x, a.y + b.y}; x[ib] = cf{a.x - b.x, a.y - b.y}; } }
; }
; __device__ __forceinline__ void lds_barrier() { asm volatile("s_waitcnt lgkmcnt(0)\n\ts_barrier" ::: "memory"); }
; template <int LR, bool INV> __device__ __forceinline__ void fft_pass(ldsf2 buf, int base, int stride, int twi) {
;     constexpr int R = 1 << LR; cf x[R];
;     const v2f wv = ((ldsf2)((LAS unsigned char*)buf + 139264))[twi];
; #pragma unroll
;     for (int m = 0; m < R; ++m) { const v2f v = buf[base + m * stride]; x[m] = cf{v.x, v.y}; }
;     const cf w{wv.x, wv.y};
;     if (INV) dit_reg<LR>(x, w); else dif_reg<LR>(x, w);
; #pragma unroll
;     for (int m = 0; m < R; ++m) buf[base + m * stride] = mkv2(x[m].x, x[m].y);
; }
; __device__ __forceinline__ void fft_conv(ldsf2 buf, const LAS unsigned* spec) {
;     fft_fwd_abc(buf);
;     { const int tid = otid(); cf x[16];
; #pragma unroll
;       for (int m = 0; m < 16; ++m) { const v2f v = buf[tid * 17 + m]; x[m] = cf{v.x, v.y}; }
;       dif_reg<4>(x, cf{1.0f, 0.0f});
	v_pk_add_f32 v[152:153], v[124:125], v[132:133] neg_lo:[0,1] neg_hi:[0,1]
	v_pk_add_f32 v[154:155], v[126:127], v[134:135] neg_lo:[0,1] neg_hi:[0,1]
	v_pk_add_f32 v[156:157], v[128:129], v[148:149] neg_lo:[0,1] neg_hi:[0,1]
	v_pk_add_f32 v[158:159], v[130:131], v[150:151] neg_lo:[0,1] neg_hi:[0,1]
	v_pk_add_f32 v[124:125], v[124:125], v[132:133]
	v_pk_add_f32 v[126:127], v[126:127], v[134:135]
	v_pk_add_f32 v[128:129], v[128:129], v[148:149]
	v_pk_add_f32 v[130:131], v[130:131], v[150:151]
	v_pk_mul_f32 v[132:133], v[152:153], v[90:91] op_sel:[1,1] op_sel_hi:[1,0]
	v_pk_mul_f32 v[134:135], v[154:155], v[94:95] op_sel:[1,1] op_sel_hi:[1,0]
	v_pk_mul_f32 v[148:149], v[156:157], v[90:91] op_sel:[1,0] op_sel_hi:[1,1]
	v_pk_mul_f32 v[150:151], v[158:159], v[96:97] op_sel:[1,1] op_sel_hi:[1,0]
	v_pk_fma_f32 v[132:133], v[152:153], v[90:91], v[132:133] op_sel:[0,0,0] op_sel_hi:[0,1,1] neg_lo:[0,0,1] neg_hi:[0,0,0]
	v_pk_fma_f32 v[134:135], v[154:155], v[94:95], v[134:135] op_sel:[0,0,0] op_sel_hi:[0,1,1] neg_lo:[0,0,1] neg_hi:[0,0,0]
	v_pk_fma_f32 v[148:149], v[156:157], v[90:91], v[148:149] op_sel:[0,1,0] op_sel_hi:[0,0,1] neg_lo:[0,0,0] neg_hi:[0,1,0]
	v_pk_fma_f32 v[150:151], v[158:159], v[96:97], v[150:151] op_sel:[0,0,0] op_sel_hi:[0,1,1] neg_lo:[0,0,1] neg_hi:[0,0,0]
	v_pk_add_f32 v[152:153], v[124:125], v[128:129] neg_lo:[0,1] neg_hi:[0,1]
	v_pk_add_f32 v[154:155], v[126:127], v[130:131] neg_lo:[0,1] neg_hi:[0,1]
	v_pk_add_f32 v[156:157], v[132:133], v[148:149] neg_lo:[0,1] neg_hi:[0,1]
	v_pk_add_f32 v[158:159], v[134:135], v[150:151] neg_lo:[0,1] neg_hi:[0,1]
	v_pk_add_f32 v[124:125], v[124:125], v[128:129]
	v_pk_add_f32 v[126:127], v[126:127], v[130:131]
	v_pk_add_f32 v[132:133], v[132:133], v[148:149]
	v_pk_add_f32 v[134:135], v[134:135], v[150:151]
	v_pk_mul_f32 v[128:129], v[152:153], v[98:99] op_sel:[1,1] op_sel_hi:[1,0]
	v_pk_mul_f32 v[130:131], v[154:155], v[98:99] op_sel:[1,0] op_sel_hi:[1,1]
	v_pk_mul_f32 v[148:149], v[156:157], v[98:99] op_sel:[1,1] op_sel_hi:[1,0]
	v_pk_mul_f32 v[150:151], v[158:159], v[98:99] op_sel:[1,0] op_sel_hi:[1,1]
	v_pk_fma_f32 v[128:129], v[152:153], v[98:99], v[128:129] op_sel:[0,0,0] op_sel_hi:[0,1,1] neg_lo:[0,0,1] neg_hi:[0,0,0]
	v_pk_fma_f32 v[130:131], v[154:155], v[98:99], v[130:131] op_sel:[0,1,0] op_sel_hi:[0,0,1] neg_lo:[0,0,0] neg_hi:[0,1,0]
	v_pk_fma_f32 v[148:149], v[156:157], v[98:99], v[148:149] op_sel:[0,0,0] op_sel_hi:[0,1,1] neg_lo:[0,0,1] neg_hi:[0,0,0]
	v_pk_fma_f32 v[150:151], v[158:159], v[98:99], v[150:151] op_sel:[0,1,0] op_sel_hi:[0,0,1] neg_lo:[0,0,0] neg_hi:[0,1,0]
	v_pk_add_f32 v[152:153], v[124:125], v[126:127] neg_lo:[0,1] neg_hi:[0,1]
	v_pk_add_f32 v[154:155], v[128:129], v[130:131] neg_lo:[0,1] neg_hi:[0,1]
	v_pk_add_f32 v[156:157], v[132:133], v[134:135] neg_lo:[0,1] neg_hi:[0,1]
	v_pk_add_f32 v[158:159], v[148:149], v[150:151] neg_lo:[0,1] neg_hi:[0,1]
	v_pk_add_f32 v[124:125], v[124:125], v[126:127]
	v_pk_add_f32 v[128:129], v[128:129], v[130:131]
	v_pk_add_f32 v[132:133], v[132:133], v[134:135]
	v_pk_add_f32 v[148:149], v[148:149], v[150:151]
	v_pk_mul_f32 v[126:127], v[152:153], v[100:101] op_sel:[1,1] op_sel_hi:[1,0]
	v_pk_mul_f32 v[130:131], v[154:155], v[100:101] op_sel:[1,1] op_sel_hi:[1,0]
	v_pk_mul_f32 v[134:135], v[156:157], v[100:101] op_sel:[1,1] op_sel_hi:[1,0]
	v_pk_mul_f32 v[150:151], v[158:159], v[100:101] op_sel:[1,1] op_sel_hi:[1,0]
	v_pk_fma_f32 v[126:127], v[152:153], v[100:101], v[126:127] op_sel:[0,0,0] op_sel_hi:[0,1,1] neg_lo:[0,0,1] neg_hi:[0,0,0]
	v_pk_fma_f32 v[130:131], v[154:155], v[100:101], v[130:131] op_sel:[0,0,0] op_sel_hi:[0,1,1] neg_lo:[0,0,1] neg_hi:[0,0,0]
	v_pk_fma_f32 v[134:135], v[156:157], v[100:101], v[134:135] op_sel:[0,0,0] op_sel_hi:[0,1,1] neg_lo:[0,0,1] neg_hi:[0,0,0]
	v_pk_fma_f32 v[150:151], v[158:159], v[100:101], v[150:151] op_sel:[0,0,0] op_sel_hi:[0,1,1] neg_lo:[0,0,1] neg_hi:[0,0,0]
	ds_write2_b64 v118, v[124:125], v[126:127] offset1:17
	ds_write2_b64 v118, v[128:129], v[130:131] offset0:34 offset1:51
	ds_write2_b64 v118, v[132:133], v[134:135] offset0:68 offset1:85
	ds_write2_b64 v118, v[148:149], v[150:151] offset0:102 offset1:119
	s_mov_b64 s[6:7], 0
	v_mov_b32_e32 v158, v195
	s_movk_i32 s0, 0x88
	s_waitcnt lgkmcnt(0)
	s_mov_b32 s86, s63
	v_mul_lo_u32 v68, v158, s0
	v_add_u32_e32 v147, 0, v68
	ds_read2_b64 v[72:75], v147 offset1:1
	ds_read2_b64 v[76:79], v147 offset0:2 offset1:3
	ds_read2_b64 v[90:93], v147 offset0:4 offset1:5
	ds_read2_b64 v[94:97], v147 offset0:6 offset1:7
	ds_read2_b64 v[98:101], v147 offset0:8 offset1:9
	ds_read2_b64 v[102:105], v147 offset0:10 offset1:11
	ds_read2_b64 v[118:121], v147 offset0:12 offset1:13
	ds_read2_b64 v[126:129], v147 offset0:14 offset1:15
	s_mov_b32 s6, s63
	s_mov_b32 s7, s16
	s_mov_b32 s17, s5
	s_mov_b32 s0, s16
	s_mov_b32 s1, s4
	s_mov_b32 s0, s63
	s_mov_b32 s1, s5
	s_mov_b32 s0, s87
	s_mov_b32 s1, s4
	s_mov_b32 s1, s5
	s_mov_b32 s35, s4
	s_mov_b32 s12, s63
	s_movk_i32 s0, 0x44
	v_mul_lo_u32 v106, v158, s0
	v_add_u32_e32 v106, 0, v106
	v_add_u32_e32 v106, 0x11000, v106
	ds_read2_b32 v[156:157], v106 offset1:1
	ds_read2_b32 v[158:159], v106 offset0:2 offset1:3
	ds_read2_b32 v[160:161], v106 offset0:4 offset1:5
	ds_read2_b32 v[162:163], v106 offset0:6 offset1:7
	ds_read2_b32 v[164:165], v106 offset0:8 offset1:9
	ds_read2_b32 v[134:135], v106 offset0:10 offset1:11
	ds_read2_b32 v[130:131], v106 offset0:12 offset1:13
	ds_read2_b32 v[168:169], v106 offset0:14 offset1:15
	s_mov_b32 s0, s5
	s_mov_b64 s[6:7], -1
	s_mov_b32 s35, s13
	s_mov_b32 s0, s13
	s_waitcnt lgkmcnt(8)
; __device__ __forceinline__ cf twc(cf ws, int k16) { if (k16 == 0) return ws; if (k16 == 4) return cf{ws.y, -ws.x}; return cmul(ws, cf{c16(k16), -s16(k16)}); }
; template <int LR> __device__ __forceinline__ void dif_reg(cf (&x)[1 << LR], cf w) {
;     constexpr int R = 1 << LR; cf ws = w;
; #pragma unroll
;     for (int s = 0; s < LR; ++s) { const int half = R >> (s + 1);
; #pragma unroll
;         for (int m0 = 0; m0 < R; m0 += 2 * half)
; #pragma unroll
;             for (int mm = 0; mm < half; ++mm) { const int ia = m0 + mm, ib = ia + half; const cf a = x[ia], b = x[ib];
;                 x[ia] = cf{a.x + b.x, a.y + b.y}; const cf d{a.x - b.x, a.y - b.y};
;                 x[ib] = cmul(d, twc(ws, (mm << s) * (16 / R))); }
;         ws = cmul(ws, ws); }
; }
	v_pk_add_f32 v[80:81], v[72:73], v[98:99]
	v_pk_add_f32 v[82:83], v[74:75], v[100:101]
	v_pk_add_f32 v[84:85], v[76:77], v[102:103]
	v_pk_add_f32 v[86:87], v[78:79], v[104:105]
	v_pk_add_f32 v[72:73], v[72:73], v[98:99] neg_lo:[0,1] neg_hi:[0,1]
	v_pk_add_f32 v[74:75], v[74:75], v[100:101] neg_lo:[0,1] neg_hi:[0,1]
	v_pk_add_f32 v[76:77], v[76:77], v[102:103] neg_lo:[0,1] neg_hi:[0,1]
	v_pk_add_f32 v[78:79], v[78:79], v[104:105] neg_lo:[0,1] neg_hi:[0,1]
	v_pk_mul_f32 v[100:101], v[74:75], s[4:5] op_sel:[1,1] op_sel_hi:[1,0] neg_lo:[0,1] neg_hi:[0,0]
	v_pk_mul_f32 v[102:103], v[76:77], s[16:17] op_sel:[1,0] op_sel_hi:[1,0] neg_lo:[0,1] neg_hi:[0,0]
	v_pk_mul_f32 v[104:105], v[78:79], s[4:5] op_sel:[1,0] op_sel_hi:[1,1] neg_lo:[0,1] neg_hi:[0,0]
	v_pk_fma_f32 v[100:101], v[74:75], s[4:5], v[100:101] op_sel:[0,0,0] op_sel_hi:[0,1,1] neg_lo:[0,0,1] neg_hi:[0,1,0]
	v_pk_fma_f32 v[102:103], v[76:77], s[16:17], v[102:103] op_sel:[0,0,0] op_sel_hi:[0,0,1] neg_lo:[0,0,1] neg_hi:[0,1,0]
	v_pk_fma_f32 v[104:105], v[78:79], s[4:5], v[104:105] op_sel:[0,1,0] op_sel_hi:[0,0,1] neg_lo:[0,0,1] neg_hi:[0,1,0]
	v_pk_add_f32 v[88:89], v[90:91], v[118:119]
	v_pk_add_f32 v[108:109], v[92:93], v[120:121]
	v_pk_add_f32 v[110:111], v[94:95], v[126:127]
	v_pk_add_f32 v[112:113], v[96:97], v[128:129]
	v_pk_add_f32 v[90:91], v[90:91], v[118:119] op_sel:[1,1] op_sel_hi:[0,0] neg_lo:[0,1] neg_hi:[1,0]
	v_pk_add_f32 v[92:93], v[92:93], v[120:121] neg_lo:[0,1] neg_hi:[0,1]
	v_pk_add_f32 v[94:95], v[94:95], v[126:127] neg_lo:[0,1] neg_hi:[0,1]
	v_pk_add_f32 v[96:97], v[96:97], v[128:129] neg_lo:[0,1] neg_hi:[0,1]
	v_pk_mul_f32 v[120:121], v[92:93], s[4:5] op_sel:[1,0] op_sel_hi:[1,1] neg_lo:[0,1] neg_hi:[0,1]
	v_pk_mul_f32 v[126:127], v[94:95], s[16:17] op_sel:[1,0] op_sel_hi:[1,0] neg_lo:[0,1] neg_hi:[0,1]
	v_pk_mul_f32 v[128:129], v[96:97], s[4:5] op_sel:[1,1] op_sel_hi:[1,0] neg_lo:[0,1] neg_hi:[0,1]
	v_pk_fma_f32 v[120:121], v[92:93], s[4:5], v[120:121] op_sel:[0,1,0] op_sel_hi:[0,0,1] neg_lo:[0,1,1] neg_hi:[0,1,0]
	v_pk_fma_f32 v[126:127], v[94:95], s[16:17], v[126:127] op_sel:[0,0,0] op_sel_hi:[0,0,1] neg_lo:[0,1,1] neg_hi:[0,1,0]
	v_pk_fma_f32 v[128:129], v[96:97], s[4:5], v[128:129] op_sel:[0,0,0] op_sel_hi:[0,1,1] neg_lo:[0,1,1] neg_hi:[0,1,0]
	v_pk_add_f32 v[114:115], v[80:81], v[88:89]
	v_pk_add_f32 v[116:117], v[82:83], v[108:109]
	v_pk_add_f32 v[122:123], v[84:85], v[110:111]
	v_pk_add_f32 v[124:125], v[86:87], v[112:113]
	v_pk_add_f32 v[80:81], v[80:81], v[88:89] neg_lo:[0,1] neg_hi:[0,1]
	v_pk_add_f32 v[82:83], v[82:83], v[108:109] neg_lo:[0,1] neg_hi:[0,1]
	v_pk_add_f32 v[84:85], v[84:85], v[110:111] op_sel:[1,1] op_sel_hi:[0,0] neg_lo:[0,1] neg_hi:[1,0]
	v_pk_add_f32 v[86:87], v[86:87], v[112:113] neg_lo:[0,1] neg_hi:[0,1]
	v_pk_mul_f32 v[108:109], v[82:83], s[16:17] op_sel:[1,0] op_sel_hi:[1,0] neg_lo:[0,1] neg_hi:[0,0]
	v_pk_mul_f32 v[112:113], v[86:87], s[16:17] op_sel:[1,0] op_sel_hi:[1,0] neg_lo:[0,1] neg_hi:[0,1]
	v_pk_fma_f32 v[108:109], v[82:83], s[16:17], v[108:109] op_sel:[0,0,0] op_sel_hi:[0,0,1] neg_lo:[0,0,1] neg_hi:[0,1,0]
	v_pk_fma_f32 v[112:113], v[86:87], s[16:17], v[112:113] op_sel:[0,0,0] op_sel_hi:[0,0,1] neg_lo:[0,1,1] neg_hi:[0,1,0]
	v_pk_add_f32 v[132:133], v[72:73], v[90:91]
	v_pk_add_f32 v[148:149], v[100:101], v[120:121]
	v_pk_add_f32 v[150:151], v[102:103], v[126:127]
	v_pk_add_f32 v[152:153], v[104:105], v[128:129]
	v_pk_add_f32 v[72:73], v[72:73], v[90:91] neg_lo:[0,1] neg_hi:[0,1]
	v_pk_add_f32 v[100:101], v[100:101], v[120:121] neg_lo:[0,1] neg_hi:[0,1]
	v_pk_add_f32 v[102:103], v[102:103], v[126:127] op_sel:[1,1] op_sel_hi:[0,0] neg_lo:[0,1] neg_hi:[1,0]
	v_pk_add_f32 v[104:105], v[104:105], v[128:129] neg_lo:[0,1] neg_hi:[0,1]
	v_pk_mul_f32 v[120:121], v[100:101], s[16:17] op_sel:[1,0] op_sel_hi:[1,0] neg_lo:[0,1] neg_hi:[0,0]
	v_pk_mul_f32 v[128:129], v[104:105], s[16:17] op_sel:[1,0] op_sel_hi:[1,0] neg_lo:[0,1] neg_hi:[0,1]
	v_pk_fma_f32 v[120:121], v[100:101], s[16:17], v[120:121] op_sel:[0,0,0] op_sel_hi:[0,0,1] neg_lo:[0,0,1] neg_hi:[0,1,0]
	v_pk_fma_f32 v[128:129], v[104:105], s[16:17], v[128:129] op_sel:[0,0,0] op_sel_hi:[0,0,1] neg_lo:[0,1,1] neg_hi:[0,1,0]
	v_pk_add_f32 v[154:155], v[114:115], v[122:123]
	v_pk_add_f32 v[166:167], v[116:117], v[124:125]
	v_pk_add_f32 v[98:99], v[80:81], v[84:85]
	v_pk_add_f32 v[74:75], v[108:109], v[112:113]
	v_pk_add_f32 v[114:115], v[114:115], v[122:123] neg_lo:[0,1] neg_hi:[0,1]
	v_pk_add_f32 v[116:117], v[116:117], v[124:125] op_sel:[1,1] op_sel_hi:[0,0] neg_lo:[0,1] neg_hi:[1,0]
	v_pk_add_f32 v[80:81], v[80:81], v[84:85] neg_lo:[0,1] neg_hi:[0,1]
	v_pk_add_f32 v[108:109], v[108:109], v[112:113] op_sel:[1,1] op_sel_hi:[0,0] neg_lo:[0,1] neg_hi:[1,0]
	v_pk_add_f32 v[76:77], v[132:133], v[150:151]
	v_pk_add_f32 v[78:79], v[148:149], v[152:153]
	v_pk_add_f32 v[118:119], v[72:73], v[102:103]
	v_pk_add_f32 v[92:93], v[120:121], v[128:129]
	v_pk_add_f32 v[132:133], v[132:133], v[150:151] neg_lo:[0,1] neg_hi:[0,1]
	v_pk_add_f32 v[148:149], v[148:149], v[152:153] op_sel:[1,1] op_sel_hi:[0,0] neg_lo:[0,1] neg_hi:[1,0]
	v_pk_add_f32 v[72:73], v[72:73], v[102:103] neg_lo:[0,1] neg_hi:[0,1]
	v_pk_add_f32 v[120:121], v[120:121], v[128:129] op_sel:[1,1] op_sel_hi:[0,0] neg_lo:[0,1] neg_hi:[1,0]
	v_pk_add_f32 v[94:95], v[154:155], v[166:167]
	v_pk_add_f32 v[96:97], v[114:115], v[116:117]
	v_pk_add_f32 v[88:89], v[98:99], v[74:75]
	v_pk_add_f32 v[82:83], v[80:81], v[108:109]
	v_pk_add_f32 v[154:155], v[154:155], v[166:167] neg_lo:[0,1] neg_hi:[0,1]
	v_pk_add_f32 v[114:115], v[114:115], v[116:117] neg_lo:[0,1] neg_hi:[0,1]
	v_pk_add_f32 v[98:99], v[98:99], v[74:75] neg_lo:[0,1] neg_hi:[0,1]
	v_pk_add_f32 v[80:81], v[80:81], v[108:109] neg_lo:[0,1] neg_hi:[0,1]
	v_pk_add_f32 v[110:111], v[76:77], v[78:79]
	v_pk_add_f32 v[86:87], v[132:133], v[148:149]
	v_pk_add_f32 v[90:91], v[118:119], v[92:93]
	v_pk_add_f32 v[100:101], v[72:73], v[120:121]
	v_pk_add_f32 v[76:77], v[76:77], v[78:79] neg_lo:[0,1] neg_hi:[0,1]
	v_pk_add_f32 v[132:133], v[132:133], v[148:149] neg_lo:[0,1] neg_hi:[0,1]
	v_pk_add_f32 v[118:119], v[118:119], v[92:93] neg_lo:[0,1] neg_hi:[0,1]
	v_pk_add_f32 v[72:73], v[72:73], v[120:121] neg_lo:[0,1] neg_hi:[0,1]
	s_waitcnt lgkmcnt(0)
; #define LAS __attribute__((address_space(3)))
; __device__ __forceinline__ int otid() { int t = threadIdx.x; asm volatile("" : "+v"(t)); return t; }
; __device__ __forceinline__ void fft_conv(ldsf2 buf, const LAS unsigned* spec) {
;     fft_fwd_abc(buf);
;     { const int tid = otid(); cf x[16];
; #pragma unroll
;       for (int m = 0; m < 16; ++m) { const v2f v = buf[tid * 17 + m]; x[m] = cf{v.x, v.y}; }
;       dif_reg<4>(x, cf{1.0f, 0.0f});
; #pragma unroll
;       for (int m = 0; m < 16; ++m) { const h2_t hv = __builtin_bit_cast(h2_t, spec[tid * 17 + m]); x[m] = cmul(x[m], cf{(float)hv.x, (float)hv.y}); }
;       dit_reg<4>(x, cf{1.0f, 0.0f});
; #pragma unroll
	v_cvt_f32_f16_e32 v126, v156
	v_cvt_f32_f16_e32 v122, v157
	v_cvt_f32_f16_e32 v84, v158
	v_cvt_f32_f16_e32 v150, v159
	v_cvt_f32_f16_sdwa v127, v156 dst_sel:DWORD dst_unused:UNUSED_PAD src0_sel:WORD_1
	v_cvt_f32_f16_sdwa v123, v157 dst_sel:DWORD dst_unused:UNUSED_PAD src0_sel:WORD_1
	v_cvt_f32_f16_sdwa v85, v158 dst_sel:DWORD dst_unused:UNUSED_PAD src0_sel:WORD_1
	v_cvt_f32_f16_sdwa v151, v159 dst_sel:DWORD dst_unused:UNUSED_PAD src0_sel:WORD_1
	v_pk_mul_f32 v[104:105], v[94:95], v[126:127] op_sel:[1,1] op_sel_hi:[1,0]
	v_pk_mul_f32 v[124:125], v[154:155], v[122:123] op_sel:[1,1] op_sel_hi:[1,0]
	v_pk_mul_f32 v[112:113], v[96:97], v[84:85] op_sel:[1,1] op_sel_hi:[1,0]
	v_pk_mul_f32 v[152:153], v[114:115], v[150:151] op_sel:[1,1] op_sel_hi:[1,0]
	v_pk_fma_f32 v[126:127], v[94:95], v[126:127], v[104:105] op_sel:[0,0,0] op_sel_hi:[0,1,1] neg_lo:[0,0,1] neg_hi:[0,0,0]
	v_pk_fma_f32 v[122:123], v[154:155], v[122:123], v[124:125] op_sel:[0,0,0] op_sel_hi:[0,1,1] neg_lo:[0,0,1] neg_hi:[0,0,0]
	v_pk_fma_f32 v[84:85], v[96:97], v[84:85], v[112:113] op_sel:[0,0,0] op_sel_hi:[0,1,1] neg_lo:[0,0,1] neg_hi:[0,0,0]
	v_pk_fma_f32 v[150:151], v[114:115], v[150:151], v[152:153] op_sel:[0,0,0] op_sel_hi:[0,1,1] neg_lo:[0,0,1] neg_hi:[0,0,0]
	v_cvt_f32_f16_e32 v102, v160
	v_cvt_f32_f16_e32 v166, v161
	v_cvt_f32_f16_e32 v74, v162
	v_cvt_f32_f16_e32 v78, v163
	v_cvt_f32_f16_sdwa v103, v160 dst_sel:DWORD dst_unused:UNUSED_PAD src0_sel:WORD_1
	v_cvt_f32_f16_sdwa v167, v161 dst_sel:DWORD dst_unused:UNUSED_PAD src0_sel:WORD_1
	v_cvt_f32_f16_sdwa v75, v162 dst_sel:DWORD dst_unused:UNUSED_PAD src0_sel:WORD_1
	v_cvt_f32_f16_sdwa v79, v163 dst_sel:DWORD dst_unused:UNUSED_PAD src0_sel:WORD_1
	v_pk_mul_f32 v[128:129], v[88:89], v[102:103] op_sel:[1,1] op_sel_hi:[1,0]
	v_pk_mul_f32 v[116:117], v[98:99], v[166:167] op_sel:[1,1] op_sel_hi:[1,0]
	v_pk_mul_f32 v[108:109], v[82:83], v[74:75] op_sel:[1,1] op_sel_hi:[1,0]
	v_pk_mul_f32 v[148:149], v[80:81], v[78:79] op_sel:[1,1] op_sel_hi:[1,0]
	v_pk_fma_f32 v[102:103], v[88:89], v[102:103], v[128:129] op_sel:[0,0,0] op_sel_hi:[0,1,1] neg_lo:[0,0,1] neg_hi:[0,0,0]
	v_pk_fma_f32 v[166:167], v[98:99], v[166:167], v[116:117] op_sel:[0,0,0] op_sel_hi:[0,1,1] neg_lo:[0,0,1] neg_hi:[0,0,0]
	v_pk_fma_f32 v[74:75], v[82:83], v[74:75], v[108:109] op_sel:[0,0,0] op_sel_hi:[0,1,1] neg_lo:[0,0,1] neg_hi:[0,0,0]
	v_pk_fma_f32 v[78:79], v[80:81], v[78:79], v[148:149] op_sel:[0,0,0] op_sel_hi:[0,1,1] neg_lo:[0,0,1] neg_hi:[0,0,0]
	v_cvt_f32_f16_e32 v92, v164
	v_cvt_f32_f16_e32 v104, v165
	v_cvt_f32_f16_e32 v124, v134
	v_cvt_f32_f16_e32 v112, v135
	v_cvt_f32_f16_sdwa v93, v164 dst_sel:DWORD dst_unused:UNUSED_PAD src0_sel:WORD_1
	v_cvt_f32_f16_sdwa v105, v165 dst_sel:DWORD dst_unused:UNUSED_PAD src0_sel:WORD_1
	v_cvt_f32_f16_sdwa v125, v134 dst_sel:DWORD dst_unused:UNUSED_PAD src0_sel:WORD_1
	v_cvt_f32_f16_sdwa v113, v135 dst_sel:DWORD dst_unused:UNUSED_PAD src0_sel:WORD_1
	v_pk_mul_f32 v[120:121], v[110:111], v[92:93] op_sel:[1,1] op_sel_hi:[1,0]
	v_pk_mul_f32 v[94:95], v[76:77], v[104:105] op_sel:[1,1] op_sel_hi:[1,0]
	v_pk_mul_f32 v[154:155], v[86:87], v[124:125] op_sel:[1,1] op_sel_hi:[1,0]
	v_pk_mul_f32 v[96:97], v[132:133], v[112:113] op_sel:[1,1] op_sel_hi:[1,0]
	v_pk_fma_f32 v[92:93], v[110:111], v[92:93], v[120:121] op_sel:[0,0,0] op_sel_hi:[0,1,1] neg_lo:[0,0,1] neg_hi:[0,0,0]
	v_pk_fma_f32 v[104:105], v[76:77], v[104:105], v[94:95] op_sel:[0,0,0] op_sel_hi:[0,1,1] neg_lo:[0,0,1] neg_hi:[0,0,0]
	v_pk_fma_f32 v[124:125], v[86:87], v[124:125], v[154:155] op_sel:[0,0,0] op_sel_hi:[0,1,1] neg_lo:[0,0,1] neg_hi:[0,0,0]
	v_pk_fma_f32 v[112:113], v[132:133], v[112:113], v[96:97] op_sel:[0,0,0] op_sel_hi:[0,1,1] neg_lo:[0,0,1] neg_hi:[0,0,0]
	v_cvt_f32_f16_e32 v152, v130
	v_cvt_f32_f16_e32 v128, v131
	v_cvt_f32_f16_e32 v116, v168
	v_cvt_f32_f16_e32 v108, v169
	v_cvt_f32_f16_sdwa v153, v130 dst_sel:DWORD dst_unused:UNUSED_PAD src0_sel:WORD_1
	v_cvt_f32_f16_sdwa v129, v131 dst_sel:DWORD dst_unused:UNUSED_PAD src0_sel:WORD_1
	v_cvt_f32_f16_sdwa v117, v168 dst_sel:DWORD dst_unused:UNUSED_PAD src0_sel:WORD_1
	v_cvt_f32_f16_sdwa v109, v169 dst_sel:DWORD dst_unused:UNUSED_PAD src0_sel:WORD_1
	v_pk_mul_f32 v[114:115], v[90:91], v[152:153] op_sel:[1,1] op_sel_hi:[1,0]
	v_pk_mul_f32 v[88:89], v[118:119], v[128:129] op_sel:[1,1] op_sel_hi:[1,0]
	v_pk_mul_f32 v[98:99], v[100:101], v[116:117] op_sel:[1,1] op_sel_hi:[1,0]
	v_pk_mul_f32 v[82:83], v[72:73], v[108:109] op_sel:[1,1] op_sel_hi:[1,0]
	v_pk_fma_f32 v[152:153], v[90:91], v[152:153], v[114:115] op_sel:[0,0,0] op_sel_hi:[0,1,1] neg_lo:[0,0,1] neg_hi:[0,0,0]
	v_pk_fma_f32 v[128:129], v[118:119], v[128:129], v[88:89] op_sel:[0,0,0] op_sel_hi:[0,1,1] neg_lo:[0,0,1] neg_hi:[0,0,0]
	v_pk_fma_f32 v[116:117], v[100:101], v[116:117], v[98:99] op_sel:[0,0,0] op_sel_hi:[0,1,1] neg_lo:[0,0,1] neg_hi:[0,0,0]
	v_pk_fma_f32 v[108:109], v[72:73], v[108:109], v[82:83] op_sel:[0,0,0] op_sel_hi:[0,1,1] neg_lo:[0,0,1] neg_hi:[0,0,0]
	v_pk_add_f32 v[148:149], v[126:127], v[122:123]
	v_pk_add_f32 v[80:81], v[84:85], v[150:151]
	v_pk_add_f32 v[120:121], v[102:103], v[166:167]
	v_pk_add_f32 v[110:111], v[74:75], v[78:79]
	v_pk_add_f32 v[126:127], v[126:127], v[122:123] neg_lo:[0,1] neg_hi:[0,1]
	v_pk_add_f32 v[84:85], v[84:85], v[150:151] neg_lo:[0,1] neg_hi:[0,1]
	v_pk_add_f32 v[102:103], v[102:103], v[166:167] neg_lo:[0,1] neg_hi:[0,1]
	v_pk_add_f32 v[74:75], v[74:75], v[78:79] neg_lo:[0,1] neg_hi:[0,1]
	v_pk_add_f32 v[94:95], v[92:93], v[104:105]
	v_pk_add_f32 v[76:77], v[124:125], v[112:113]
	v_pk_add_f32 v[154:155], v[152:153], v[128:129]
	v_pk_add_f32 v[86:87], v[116:117], v[108:109]
; __device__ __forceinline__ cf twc(cf ws, int k16) { if (k16 == 0) return ws; if (k16 == 4) return cf{ws.y, -ws.x}; return cmul(ws, cf{c16(k16), -s16(k16)}); }
; __device__ __forceinline__ void wave_lds_fence() { asm volatile("s_waitcnt lgkmcnt(0)" ::: "memory"); }
; template <int LR> __device__ __forceinline__ void dit_reg(cf (&x)[1 << LR], cf w) {
;     constexpr int R = 1 << LR; cf wsv[LR]; wsv[0] = w;
; #pragma unroll
;     for (int s = 1; s < LR; ++s) wsv[s] = cmul(wsv[s - 1], wsv[s - 1]);
; #pragma unroll
;     for (int s = LR - 1; s >= 0; --s) { const int half = R >> (s + 1);
; #pragma unroll
;         for (int m0 = 0; m0 < R; m0 += 2 * half)
; #pragma unroll
;             for (int mm = 0; mm < half; ++mm) { const int ia = m0 + mm, ib = ia + half; const cf a = x[ia];
;                 const cf b = cmulc(x[ib], twc(wsv[s], (mm << s) * (16 / R)));
;                 x[ia] = cf{a.x + b.x, a.y + b.y}; x[ib] = cf{a.x - b.x, a.y - b.y}; } }
; }
; __device__ __forceinline__ void fft_conv(ldsf2 buf, const LAS unsigned* spec) {
;     ...
;       dit_reg<4>(x, cf{1.0f, 0.0f});
; #pragma unroll
;       for (int m = 0; m < 16; ++m) buf[tid * 17 + m] = mkv2(x[m].x, x[m].y); }
;     wave_lds_fence();
	v_pk_add_f32 v[92:93], v[92:93], v[104:105] neg_lo:[0,1] neg_hi:[0,1]
	v_pk_add_f32 v[124:125], v[124:125], v[112:113] neg_lo:[0,1] neg_hi:[0,1]
	v_pk_add_f32 v[152:153], v[152:153], v[128:129] neg_lo:[0,1] neg_hi:[0,1]
	v_pk_add_f32 v[116:117], v[116:117], v[108:109] neg_lo:[0,1] neg_hi:[0,1]
	v_pk_add_f32 v[96:97], v[148:149], v[80:81]
	v_pk_add_f32 v[132:133], v[126:127], v[84:85] op_sel:[0,1] op_sel_hi:[1,0] neg_lo:[0,1] neg_hi:[0,0]
	v_pk_add_f32 v[114:115], v[120:121], v[110:111]
	v_pk_add_f32 v[90:91], v[102:103], v[74:75] op_sel:[0,1] op_sel_hi:[1,0] neg_lo:[0,1] neg_hi:[0,0]
	v_pk_add_f32 v[148:149], v[148:149], v[80:81] neg_lo:[0,1] neg_hi:[0,1]
	v_pk_add_f32 v[126:127], v[126:127], v[84:85] op_sel:[0,1] op_sel_hi:[1,0] neg_lo:[0,0] neg_hi:[0,1]
	v_pk_add_f32 v[120:121], v[120:121], v[110:111] neg_lo:[0,1] neg_hi:[0,1]
	v_pk_add_f32 v[102:103], v[102:103], v[74:75] op_sel:[0,1] op_sel_hi:[1,0] neg_lo:[0,0] neg_hi:[0,1]
	v_pk_add_f32 v[88:89], v[94:95], v[76:77]
	v_pk_add_f32 v[118:119], v[92:93], v[124:125] op_sel:[0,1] op_sel_hi:[1,0] neg_lo:[0,1] neg_hi:[0,0]
	v_pk_add_f32 v[98:99], v[154:155], v[86:87]
	v_pk_add_f32 v[100:101], v[152:153], v[116:117] op_sel:[0,1] op_sel_hi:[1,0] neg_lo:[0,1] neg_hi:[0,0]
	v_pk_add_f32 v[94:95], v[94:95], v[76:77] neg_lo:[0,1] neg_hi:[0,1]
	v_pk_add_f32 v[92:93], v[92:93], v[124:125] op_sel:[0,1] op_sel_hi:[1,0] neg_lo:[0,0] neg_hi:[0,1]
	v_pk_add_f32 v[154:155], v[154:155], v[86:87] neg_lo:[0,1] neg_hi:[0,1]
	v_pk_add_f32 v[152:153], v[152:153], v[116:117] op_sel:[0,1] op_sel_hi:[1,0] neg_lo:[0,0] neg_hi:[0,1]
	v_pk_add_f32 v[82:83], v[96:97], v[114:115]
	v_pk_mul_f32 v[72:73], v[90:91], s[16:17] op_sel:[1,0] op_sel_hi:[1,0] neg_lo:[0,1] neg_hi:[0,0]
	v_pk_add_f32 v[122:123], v[148:149], v[120:121] op_sel:[0,1] op_sel_hi:[1,0] neg_lo:[0,1] neg_hi:[0,0]
	v_pk_mul_f32 v[150:151], v[102:103], s[16:17] op_sel:[1,0] op_sel_hi:[1,0] neg_lo:[0,1] neg_hi:[0,1]
	v_pk_add_f32 v[96:97], v[96:97], v[114:115] neg_lo:[0,1] neg_hi:[0,1]
	v_pk_fma_f32 v[72:73], v[90:91], s[16:17], v[72:73] op_sel:[0,0,0] op_sel_hi:[0,0,1] neg_lo:[0,0,0] neg_hi:[0,0,0]
	v_pk_add_f32 v[148:149], v[148:149], v[120:121] op_sel:[0,1] op_sel_hi:[1,0] neg_lo:[0,0] neg_hi:[0,1]
	v_pk_fma_f32 v[150:151], v[102:103], s[16:17], v[150:151] op_sel:[0,0,0] op_sel_hi:[0,0,1] neg_lo:[0,1,0] neg_hi:[0,0,0]
	v_pk_add_f32 v[90:91], v[132:133], v[72:73] neg_lo:[0,1] neg_hi:[0,1]
	v_pk_add_f32 v[102:103], v[126:127], v[150:151] neg_lo:[0,1] neg_hi:[0,1]
	v_pk_add_f32 v[132:133], v[132:133], v[72:73]
	v_pk_add_f32 v[126:127], v[126:127], v[150:151]
	v_pk_add_f32 v[166:167], v[88:89], v[98:99]
	v_pk_mul_f32 v[78:79], v[100:101], s[16:17] op_sel:[1,0] op_sel_hi:[1,0] neg_lo:[0,1] neg_hi:[0,0]
	v_pk_add_f32 v[104:105], v[94:95], v[154:155] op_sel:[0,1] op_sel_hi:[1,0] neg_lo:[0,1] neg_hi:[0,0]
	v_pk_mul_f32 v[112:113], v[152:153], s[16:17] op_sel:[1,0] op_sel_hi:[1,0] neg_lo:[0,1] neg_hi:[0,1]
	v_pk_add_f32 v[88:89], v[88:89], v[98:99] neg_lo:[0,1] neg_hi:[0,1]
	v_pk_fma_f32 v[78:79], v[100:101], s[16:17], v[78:79] op_sel:[0,0,0] op_sel_hi:[0,0,1] neg_lo:[0,0,0] neg_hi:[0,0,0]
	v_pk_add_f32 v[94:95], v[94:95], v[154:155] op_sel:[0,1] op_sel_hi:[1,0] neg_lo:[0,0] neg_hi:[0,1]
	v_pk_fma_f32 v[112:113], v[152:153], s[16:17], v[112:113] op_sel:[0,0,0] op_sel_hi:[0,0,1] neg_lo:[0,1,0] neg_hi:[0,0,0]
	v_pk_add_f32 v[100:101], v[118:119], v[78:79] neg_lo:[0,1] neg_hi:[0,1]
	v_pk_add_f32 v[152:153], v[92:93], v[112:113] neg_lo:[0,1] neg_hi:[0,1]
	v_pk_add_f32 v[118:119], v[118:119], v[78:79]
	v_pk_add_f32 v[92:93], v[92:93], v[112:113]
	v_pk_add_f32 v[128:129], v[82:83], v[166:167]
	v_pk_mul_f32 v[108:109], v[118:119], s[4:5] op_sel:[1,1] op_sel_hi:[1,0] neg_lo:[0,1] neg_hi:[0,0]
	v_pk_mul_f32 v[80:81], v[104:105], s[16:17] op_sel:[1,0] op_sel_hi:[1,0] neg_lo:[0,1] neg_hi:[0,0]
	v_pk_mul_f32 v[84:85], v[92:93], s[4:5] op_sel:[1,0] op_sel_hi:[1,1] neg_lo:[0,1] neg_hi:[0,0]
	v_pk_add_f32 v[82:83], v[82:83], v[166:167] neg_lo:[0,1] neg_hi:[0,1]
	v_pk_fma_f32 v[108:109], v[118:119], s[4:5], v[108:109] op_sel:[0,0,0] op_sel_hi:[0,1,1] neg_lo:[0,0,0] neg_hi:[0,0,0]
	v_pk_fma_f32 v[80:81], v[104:105], s[16:17], v[80:81] op_sel:[0,0,0] op_sel_hi:[0,0,1] neg_lo:[0,0,0] neg_hi:[0,0,0]
	v_pk_fma_f32 v[84:85], v[92:93], s[4:5], v[84:85] op_sel:[0,1,0] op_sel_hi:[0,0,1] neg_lo:[0,0,0] neg_hi:[0,0,0]
	v_pk_add_f32 v[118:119], v[132:133], v[108:109] neg_lo:[0,1] neg_hi:[0,1]
	v_pk_add_f32 v[104:105], v[122:123], v[80:81] neg_lo:[0,1] neg_hi:[0,1]
	v_pk_add_f32 v[92:93], v[126:127], v[84:85] neg_lo:[0,1] neg_hi:[0,1]
	v_pk_add_f32 v[132:133], v[132:133], v[108:109]
	v_pk_add_f32 v[122:123], v[122:123], v[80:81]
	v_pk_add_f32 v[126:127], v[126:127], v[84:85]
	v_pk_add_f32 v[110:111], v[96:97], v[88:89] op_sel:[0,1] op_sel_hi:[1,0] neg_lo:[0,1] neg_hi:[0,0]
	v_pk_mul_f32 v[74:75], v[100:101], s[4:5] op_sel:[1,0] op_sel_hi:[1,1] neg_lo:[0,1] neg_hi:[0,1]
	v_pk_mul_f32 v[76:77], v[94:95], s[16:17] op_sel:[1,0] op_sel_hi:[1,0] neg_lo:[0,1] neg_hi:[0,1]
	v_pk_mul_f32 v[124:125], v[152:153], s[4:5] op_sel:[1,1] op_sel_hi:[1,0] neg_lo:[0,1] neg_hi:[0,1]
	v_pk_add_f32 v[96:97], v[96:97], v[88:89] op_sel:[0,1] op_sel_hi:[1,0] neg_lo:[0,0] neg_hi:[0,1]
	v_pk_fma_f32 v[74:75], v[100:101], s[4:5], v[74:75] op_sel:[0,1,0] op_sel_hi:[0,0,1] neg_lo:[0,1,0] neg_hi:[0,0,0]
	v_pk_fma_f32 v[76:77], v[94:95], s[16:17], v[76:77] op_sel:[0,0,0] op_sel_hi:[0,0,1] neg_lo:[0,1,0] neg_hi:[0,0,0]
	v_pk_fma_f32 v[124:125], v[152:153], s[4:5], v[124:125] op_sel:[0,0,0] op_sel_hi:[0,1,1] neg_lo:[0,1,0] neg_hi:[0,0,0]
	v_pk_add_f32 v[100:101], v[90:91], v[74:75] neg_lo:[0,1] neg_hi:[0,1]
	v_pk_add_f32 v[94:95], v[148:149], v[76:77] neg_lo:[0,1] neg_hi:[0,1]
	v_pk_add_f32 v[152:153], v[102:103], v[124:125] neg_lo:[0,1] neg_hi:[0,1]
	v_pk_add_f32 v[90:91], v[90:91], v[74:75]
	v_pk_add_f32 v[148:149], v[148:149], v[76:77]
	v_pk_add_f32 v[102:103], v[102:103], v[124:125]
	ds_write2_b64 v147, v[128:129], v[132:133] offset1:1
	ds_write2_b64 v147, v[122:123], v[126:127] offset0:2 offset1:3
	ds_write2_b64 v147, v[110:111], v[90:91] offset0:4 offset1:5
	ds_write2_b64 v147, v[148:149], v[102:103] offset0:6 offset1:7
	ds_write2_b64 v147, v[82:83], v[118:119] offset0:8 offset1:9
	ds_write2_b64 v147, v[104:105], v[92:93] offset0:10 offset1:11
	ds_write2_b64 v147, v[96:97], v[100:101] offset0:12 offset1:13
	ds_write2_b64 v147, v[94:95], v[152:153] offset0:14 offset1:15
	v_mov_b32_e32 v68, v195
	s_waitcnt lgkmcnt(0)
	s_mov_b32 s0, 0
	v_and_b32_e32 v73, 15, v68
	v_lshlrev_b32_e32 v72, 4, v68
	v_lshlrev_b32_e32 v75, 9, v73
	v_and_b32_e32 v72, 0xfffffc00, v72
	v_lshlrev_b32_e32 v74, 3, v68
	v_add_u32_e32 v75, 0, v75
	v_and_b32_e32 v69, 63, v68
	v_lshl_add_u32 v73, v73, 3, 0
	v_and_or_b32 v74, v74, s90, v72
	v_add_u32_e32 v75, 0x22000, v75
; #define LAS __attribute__((address_space(3)))
; __device__ __forceinline__ cf twc(cf ws, int k16) { if (k16 == 0) return ws; if (k16 == 4) return cf{ws.y, -ws.x}; return cmul(ws, cf{c16(k16), -s16(k16)}); }
; template <int LR> __device__ __forceinline__ void dit_reg(cf (&x)[1 << LR], cf w) {
;     constexpr int R = 1 << LR; cf wsv[LR]; wsv[0] = w;
; #pragma unroll
;     for (int s = 1; s < LR; ++s) wsv[s] = cmul(wsv[s - 1], wsv[s - 1]);
; #pragma unroll
;     for (int s = LR - 1; s >= 0; --s) { const int half = R >> (s + 1);
; #pragma unroll
;         for (int m0 = 0; m0 < R; m0 += 2 * half)
; #pragma unroll
;             for (int mm = 0; mm < half; ++mm) { const int ia = m0 + mm, ib = ia + half; const cf a = x[ia];
;                 const cf b = cmulc(x[ib], twc(wsv[s], (mm << s) * (16 / R)));
;                 x[ia] = cf{a.x + b.x, a.y + b.y}; x[ib] = cf{a.x - b.x, a.y - b.y}; } }
; }
; __device__ __forceinline__ void lds_barrier() { asm volatile("s_waitcnt lgkmcnt(0)\n\ts_barrier" ::: "memory"); }
; template <int LR, bool INV> __device__ __forceinline__ void fft_pass(ldsf2 buf, int base, int stride, int twi) {
;     constexpr int R = 1 << LR; cf x[R];
;     const v2f wv = ((ldsf2)((LAS unsigned char*)buf + 139264))[twi];
; #pragma unroll
;     for (int m = 0; m < R; ++m) { const v2f v = buf[base + m * stride]; x[m] = cf{v.x, v.y}; }
;     const cf w{wv.x, wv.y};
;     if (INV) dit_reg<LR>(x, w); else dif_reg<LR>(x, w);
; #pragma unroll
;     for (int m = 0; m < R; ++m) buf[base + m * stride] = mkv2(x[m].x, x[m].y);
; }
.LBB0_353:
	ds_read_b64 v[92:93], v75
	v_or_b32_e32 v76, s0, v74
	v_lshlrev_b32_e32 v77, 3, v76
	v_ashrrev_i32_e32 v76, 1, v76
	v_add3_u32 v122, v73, v77, v76
	ds_read2_b64 v[76:79], v122 offset1:17
	ds_read2_b64 v[80:83], v122 offset0:34 offset1:51
	ds_read2_b64 v[84:87], v122 offset0:68 offset1:85
	ds_read2_b64 v[88:91], v122 offset0:102 offset1:119
	s_movk_i32 s0, 0x200
	v_or_b32_e32 v126, s0, v74
	v_lshlrev_b32_e32 v128, 3, v126
	v_ashrrev_i32_e32 v126, 1, v126
	v_add3_u32 v130, v73, v128, v126
	ds_read2_b64 v[132:135], v130 offset1:17
	ds_read2_b64 v[148:151], v130 offset0:34 offset1:51
	ds_read2_b64 v[152:155], v130 offset0:68 offset1:85
	ds_read2_b64 v[156:159], v130 offset0:102 offset1:119
	s_waitcnt lgkmcnt(4)
	v_pk_add_f32 v[94:95], v[92:93], v[92:93] op_sel:[0,1] op_sel_hi:[1,0] neg_lo:[0,0] neg_hi:[0,1]
	v_pk_mul_f32 v[100:101], v[92:93], v[92:93] op_sel:[1,1] op_sel_hi:[1,0]
	v_pk_mul_f32 v[96:97], v[94:95], s[16:17] op_sel:[0,0] op_sel_hi:[1,0]
	v_pk_fma_f32 v[100:101], v[92:93], v[92:93], v[100:101] op_sel:[0,0,0] op_sel_hi:[0,1,1] neg_lo:[0,0,1] neg_hi:[0,0,0]
	v_pk_mul_f32 v[98:99], v[94:95], s[16:17] op_sel:[1,0] op_sel_hi:[0,0] neg_lo:[0,0] neg_hi:[1,0]
	s_nop 0
	v_pk_mul_f32 v[102:103], v[100:101], v[100:101] op_sel:[1,1] op_sel_hi:[1,0]
	s_nop 0
	v_pk_fma_f32 v[102:103], v[100:101], v[100:101], v[102:103] op_sel:[0,0,0] op_sel_hi:[0,1,1] neg_lo:[0,0,1] neg_hi:[0,0,0]
	v_pk_mul_f32 v[104:105], v[78:79], v[102:103] op_sel:[1,1] op_sel_hi:[1,0]
	v_pk_mul_f32 v[106:107], v[82:83], v[102:103] op_sel:[1,1] op_sel_hi:[1,0]
	v_pk_mul_f32 v[108:109], v[86:87], v[102:103] op_sel:[1,1] op_sel_hi:[1,0]
	v_pk_mul_f32 v[110:111], v[90:91], v[102:103] op_sel:[1,1] op_sel_hi:[1,0]
	v_pk_fma_f32 v[104:105], v[78:79], v[102:103], v[104:105] op_sel:[0,0,0] op_sel_hi:[0,1,1] neg_lo:[0,0,0] neg_hi:[0,1,0]
	v_pk_fma_f32 v[106:107], v[82:83], v[102:103], v[106:107] op_sel:[0,0,0] op_sel_hi:[0,1,1] neg_lo:[0,0,0] neg_hi:[0,1,0]
	v_pk_fma_f32 v[108:109], v[86:87], v[102:103], v[108:109] op_sel:[0,0,0] op_sel_hi:[0,1,1] neg_lo:[0,0,0] neg_hi:[0,1,0]
	v_pk_fma_f32 v[110:111], v[90:91], v[102:103], v[110:111] op_sel:[0,0,0] op_sel_hi:[0,1,1] neg_lo:[0,0,0] neg_hi:[0,1,0]
	v_pk_add_f32 v[78:79], v[76:77], v[104:105] neg_lo:[0,1] neg_hi:[0,1]
	v_pk_add_f32 v[82:83], v[80:81], v[106:107] neg_lo:[0,1] neg_hi:[0,1]
	v_pk_add_f32 v[86:87], v[84:85], v[108:109] neg_lo:[0,1] neg_hi:[0,1]
	v_pk_add_f32 v[90:91], v[88:89], v[110:111] neg_lo:[0,1] neg_hi:[0,1]
	v_pk_add_f32 v[76:77], v[76:77], v[104:105]
	v_pk_add_f32 v[80:81], v[80:81], v[106:107]
	v_pk_add_f32 v[84:85], v[84:85], v[108:109]
	v_pk_add_f32 v[88:89], v[88:89], v[110:111]
	v_pk_mul_f32 v[104:105], v[80:81], v[100:101] op_sel:[1,1] op_sel_hi:[1,0]
	v_pk_mul_f32 v[106:107], v[82:83], v[100:101] op_sel:[1,0] op_sel_hi:[1,1]
	v_pk_mul_f32 v[108:109], v[88:89], v[100:101] op_sel:[1,1] op_sel_hi:[1,0]
	v_pk_mul_f32 v[110:111], v[90:91], v[100:101] op_sel:[1,0] op_sel_hi:[1,1]
	v_pk_fma_f32 v[104:105], v[80:81], v[100:101], v[104:105] op_sel:[0,0,0] op_sel_hi:[0,1,1] neg_lo:[0,0,0] neg_hi:[0,1,0]
	v_pk_fma_f32 v[106:107], v[82:83], v[100:101], v[106:107] op_sel:[0,1,0] op_sel_hi:[0,0,1] neg_lo:[0,0,1] neg_hi:[0,0,0]
	v_pk_fma_f32 v[108:109], v[88:89], v[100:101], v[108:109] op_sel:[0,0,0] op_sel_hi:[0,1,1] neg_lo:[0,0,0] neg_hi:[0,1,0]
	v_pk_fma_f32 v[110:111], v[90:91], v[100:101], v[110:111] op_sel:[0,1,0] op_sel_hi:[0,0,1] neg_lo:[0,0,1] neg_hi:[0,0,0]
	v_pk_add_f32 v[80:81], v[76:77], v[104:105] neg_lo:[0,1] neg_hi:[0,1]
	v_pk_add_f32 v[82:83], v[78:79], v[106:107] neg_lo:[0,1] neg_hi:[0,1]
	v_pk_add_f32 v[88:89], v[84:85], v[108:109] neg_lo:[0,1] neg_hi:[0,1]
	v_pk_add_f32 v[90:91], v[86:87], v[110:111] neg_lo:[0,1] neg_hi:[0,1]
	v_pk_add_f32 v[76:77], v[76:77], v[104:105]
	v_pk_add_f32 v[78:79], v[78:79], v[106:107]
	v_pk_add_f32 v[84:85], v[84:85], v[108:109]
	v_pk_add_f32 v[86:87], v[86:87], v[110:111]
	v_pk_mul_f32 v[104:105], v[84:85], v[92:93] op_sel:[1,1] op_sel_hi:[1,0]
	v_pk_mul_f32 v[106:107], v[86:87], v[96:97] op_sel:[1,1] op_sel_hi:[1,0]
	v_pk_mul_f32 v[108:109], v[88:89], v[92:93] op_sel:[1,0] op_sel_hi:[1,1]
	v_pk_mul_f32 v[110:111], v[90:91], v[98:99] op_sel:[1,1] op_sel_hi:[1,0]
	v_pk_fma_f32 v[104:105], v[84:85], v[92:93], v[104:105] op_sel:[0,0,0] op_sel_hi:[0,1,1] neg_lo:[0,0,0] neg_hi:[0,1,0]
	v_pk_fma_f32 v[106:107], v[86:87], v[96:97], v[106:107] op_sel:[0,0,0] op_sel_hi:[0,1,1] neg_lo:[0,0,0] neg_hi:[0,1,0]
	v_pk_fma_f32 v[108:109], v[88:89], v[92:93], v[108:109] op_sel:[0,1,0] op_sel_hi:[0,0,1] neg_lo:[0,0,1] neg_hi:[0,0,0]
	v_pk_fma_f32 v[110:111], v[90:91], v[98:99], v[110:111] op_sel:[0,0,0] op_sel_hi:[0,1,1] neg_lo:[0,0,0] neg_hi:[0,1,0]
	v_pk_add_f32 v[84:85], v[76:77], v[104:105] neg_lo:[0,1] neg_hi:[0,1]
	v_pk_add_f32 v[86:87], v[78:79], v[106:107] neg_lo:[0,1] neg_hi:[0,1]
	v_pk_add_f32 v[88:89], v[80:81], v[108:109] neg_lo:[0,1] neg_hi:[0,1]
	v_pk_add_f32 v[90:91], v[82:83], v[110:111] neg_lo:[0,1] neg_hi:[0,1]
	v_pk_add_f32 v[76:77], v[76:77], v[104:105]
	v_pk_add_f32 v[78:79], v[78:79], v[106:107]
	v_pk_add_f32 v[80:81], v[80:81], v[108:109]
	v_pk_add_f32 v[82:83], v[82:83], v[110:111]
	ds_write2_b64 v122, v[76:77], v[78:79] offset1:17
	ds_write2_b64 v122, v[80:81], v[82:83] offset0:34 offset1:51
	ds_write2_b64 v122, v[84:85], v[86:87] offset0:68 offset1:85
	ds_write2_b64 v122, v[88:89], v[90:91] offset0:102 offset1:119
	s_waitcnt lgkmcnt(4)
; #define LAS __attribute__((address_space(3)))
; __device__ __forceinline__ int otid() { int t = threadIdx.x; asm volatile("" : "+v"(t)); return t; }
; __device__ __forceinline__ cf twc(cf ws, int k16) { if (k16 == 0) return ws; if (k16 == 4) return cf{ws.y, -ws.x}; return cmul(ws, cf{c16(k16), -s16(k16)}); }
; __device__ __forceinline__ void wave_lds_fence() { asm volatile("s_waitcnt lgkmcnt(0)" ::: "memory"); }
; template <int LR> __device__ __forceinline__ void dit_reg(cf (&x)[1 << LR], cf w) {
;     constexpr int R = 1 << LR; cf wsv[LR]; wsv[0] = w;
; #pragma unroll
;     for (int s = 1; s < LR; ++s) wsv[s] = cmul(wsv[s - 1], wsv[s - 1]);
; #pragma unroll
;     for (int s = LR - 1; s >= 0; --s) { const int half = R >> (s + 1);
; #pragma unroll
;         for (int m0 = 0; m0 < R; m0 += 2 * half)
; #pragma unroll
;             for (int mm = 0; mm < half; ++mm) { const int ia = m0 + mm, ib = ia + half; const cf a = x[ia];
;                 const cf b = cmulc(x[ib], twc(wsv[s], (mm << s) * (16 / R)));
;                 x[ia] = cf{a.x + b.x, a.y + b.y}; x[ib] = cf{a.x - b.x, a.y - b.y}; } }
; }
; __device__ __forceinline__ void lds_barrier() { asm volatile("s_waitcnt lgkmcnt(0)\n\ts_barrier" ::: "memory"); }
; template <int LR, bool INV> __device__ __forceinline__ void fft_pass(ldsf2 buf, int base, int stride, int twi) {
;     constexpr int R = 1 << LR; cf x[R];
;     const v2f wv = ((ldsf2)((LAS unsigned char*)buf + 139264))[twi];
; #pragma unroll
;     for (int m = 0; m < R; ++m) { const v2f v = buf[base + m * stride]; x[m] = cf{v.x, v.y}; }
;     const cf w{wv.x, wv.y};
;     if (INV) dit_reg<LR>(x, w); else dif_reg<LR>(x, w);
; #pragma unroll
;     for (int m = 0; m < R; ++m) buf[base + m * stride] = mkv2(x[m].x, x[m].y);
; }
; __device__ __forceinline__ void fft_inv_cba(ldsf2 buf) {
;     const int tid = otid(); const int wv = tid >> 6, l = tid & 63;
; #pragma unroll 1
;     for (int u = 0; u < 2; ++u) { const int j = l + 64 * u, o = j & 15, e0 = wv * 1024 + (j >> 4) * 128 + o; fft_pass<3, true>(buf, e0 + (e0 >> 4), 17, o * 64); }
;     wave_lds_fence();
	v_pk_mul_f32 v[160:161], v[134:135], v[102:103] op_sel:[1,1] op_sel_hi:[1,0]
	v_pk_mul_f32 v[162:163], v[150:151], v[102:103] op_sel:[1,1] op_sel_hi:[1,0]
	v_pk_mul_f32 v[164:165], v[154:155], v[102:103] op_sel:[1,1] op_sel_hi:[1,0]
	v_pk_mul_f32 v[166:167], v[158:159], v[102:103] op_sel:[1,1] op_sel_hi:[1,0]
	v_pk_fma_f32 v[160:161], v[134:135], v[102:103], v[160:161] op_sel:[0,0,0] op_sel_hi:[0,1,1] neg_lo:[0,0,0] neg_hi:[0,1,0]
	v_pk_fma_f32 v[162:163], v[150:151], v[102:103], v[162:163] op_sel:[0,0,0] op_sel_hi:[0,1,1] neg_lo:[0,0,0] neg_hi:[0,1,0]
	v_pk_fma_f32 v[164:165], v[154:155], v[102:103], v[164:165] op_sel:[0,0,0] op_sel_hi:[0,1,1] neg_lo:[0,0,0] neg_hi:[0,1,0]
	v_pk_fma_f32 v[166:167], v[158:159], v[102:103], v[166:167] op_sel:[0,0,0] op_sel_hi:[0,1,1] neg_lo:[0,0,0] neg_hi:[0,1,0]
	v_pk_add_f32 v[134:135], v[132:133], v[160:161] neg_lo:[0,1] neg_hi:[0,1]
	v_pk_add_f32 v[150:151], v[148:149], v[162:163] neg_lo:[0,1] neg_hi:[0,1]
	v_pk_add_f32 v[154:155], v[152:153], v[164:165] neg_lo:[0,1] neg_hi:[0,1]
	v_pk_add_f32 v[158:159], v[156:157], v[166:167] neg_lo:[0,1] neg_hi:[0,1]
	v_pk_add_f32 v[132:133], v[132:133], v[160:161]
	v_pk_add_f32 v[148:149], v[148:149], v[162:163]
	v_pk_add_f32 v[152:153], v[152:153], v[164:165]
	v_pk_add_f32 v[156:157], v[156:157], v[166:167]
	v_pk_mul_f32 v[160:161], v[148:149], v[100:101] op_sel:[1,1] op_sel_hi:[1,0]
	v_pk_mul_f32 v[162:163], v[150:151], v[100:101] op_sel:[1,0] op_sel_hi:[1,1]
	v_pk_mul_f32 v[164:165], v[156:157], v[100:101] op_sel:[1,1] op_sel_hi:[1,0]
	v_pk_mul_f32 v[166:167], v[158:159], v[100:101] op_sel:[1,0] op_sel_hi:[1,1]
	v_pk_fma_f32 v[160:161], v[148:149], v[100:101], v[160:161] op_sel:[0,0,0] op_sel_hi:[0,1,1] neg_lo:[0,0,0] neg_hi:[0,1,0]
	v_pk_fma_f32 v[162:163], v[150:151], v[100:101], v[162:163] op_sel:[0,1,0] op_sel_hi:[0,0,1] neg_lo:[0,0,1] neg_hi:[0,0,0]
	v_pk_fma_f32 v[164:165], v[156:157], v[100:101], v[164:165] op_sel:[0,0,0] op_sel_hi:[0,1,1] neg_lo:[0,0,0] neg_hi:[0,1,0]
	v_pk_fma_f32 v[166:167], v[158:159], v[100:101], v[166:167] op_sel:[0,1,0] op_sel_hi:[0,0,1] neg_lo:[0,0,1] neg_hi:[0,0,0]
	v_pk_add_f32 v[148:149], v[132:133], v[160:161] neg_lo:[0,1] neg_hi:[0,1]
	v_pk_add_f32 v[150:151], v[134:135], v[162:163] neg_lo:[0,1] neg_hi:[0,1]
	v_pk_add_f32 v[156:157], v[152:153], v[164:165] neg_lo:[0,1] neg_hi:[0,1]
	v_pk_add_f32 v[158:159], v[154:155], v[166:167] neg_lo:[0,1] neg_hi:[0,1]
	v_pk_add_f32 v[132:133], v[132:133], v[160:161]
	v_pk_add_f32 v[134:135], v[134:135], v[162:163]
	v_pk_add_f32 v[152:153], v[152:153], v[164:165]
	v_pk_add_f32 v[154:155], v[154:155], v[166:167]
	v_pk_mul_f32 v[160:161], v[152:153], v[92:93] op_sel:[1,1] op_sel_hi:[1,0]
	v_pk_mul_f32 v[162:163], v[154:155], v[96:97] op_sel:[1,1] op_sel_hi:[1,0]
	v_pk_mul_f32 v[164:165], v[156:157], v[92:93] op_sel:[1,0] op_sel_hi:[1,1]
	v_pk_mul_f32 v[166:167], v[158:159], v[98:99] op_sel:[1,1] op_sel_hi:[1,0]
	v_pk_fma_f32 v[160:161], v[152:153], v[92:93], v[160:161] op_sel:[0,0,0] op_sel_hi:[0,1,1] neg_lo:[0,0,0] neg_hi:[0,1,0]
	v_pk_fma_f32 v[162:163], v[154:155], v[96:97], v[162:163] op_sel:[0,0,0] op_sel_hi:[0,1,1] neg_lo:[0,0,0] neg_hi:[0,1,0]
	v_pk_fma_f32 v[164:165], v[156:157], v[92:93], v[164:165] op_sel:[0,1,0] op_sel_hi:[0,0,1] neg_lo:[0,0,1] neg_hi:[0,0,0]
	v_pk_fma_f32 v[166:167], v[158:159], v[98:99], v[166:167] op_sel:[0,0,0] op_sel_hi:[0,1,1] neg_lo:[0,0,0] neg_hi:[0,1,0]
	v_pk_add_f32 v[152:153], v[132:133], v[160:161] neg_lo:[0,1] neg_hi:[0,1]
	v_pk_add_f32 v[154:155], v[134:135], v[162:163] neg_lo:[0,1] neg_hi:[0,1]
	v_pk_add_f32 v[156:157], v[148:149], v[164:165] neg_lo:[0,1] neg_hi:[0,1]
	v_pk_add_f32 v[158:159], v[150:151], v[166:167] neg_lo:[0,1] neg_hi:[0,1]
	v_pk_add_f32 v[132:133], v[132:133], v[160:161]
	v_pk_add_f32 v[134:135], v[134:135], v[162:163]
	v_pk_add_f32 v[148:149], v[148:149], v[164:165]
	v_pk_add_f32 v[150:151], v[150:151], v[166:167]
	ds_write2_b64 v130, v[132:133], v[134:135] offset1:17
	ds_write2_b64 v130, v[148:149], v[150:151] offset0:34 offset1:51
	ds_write2_b64 v130, v[152:153], v[154:155] offset0:68 offset1:85
	ds_write2_b64 v130, v[156:157], v[158:159] offset0:102 offset1:119
	s_mov_b64 s[6:7], 0
	s_waitcnt lgkmcnt(0)
	s_mov_b32 s0, 0
	s_mov_b64 s[6:7], -1

; #define LAS __attribute__((address_space(3)))
; __device__ __forceinline__ cf twc(cf ws, int k16) { if (k16 == 0) return ws; if (k16 == 4) return cf{ws.y, -ws.x}; return cmul(ws, cf{c16(k16), -s16(k16)}); }
; template <int LR> __device__ __forceinline__ void dif_reg(cf (&x)[1 << LR], cf w) {
;     constexpr int R = 1 << LR; cf ws = w;
; #pragma unroll
;     for (int s = 0; s < LR; ++s) { const int half = R >> (s + 1);
; #pragma unroll
;         for (int m0 = 0; m0 < R; m0 += 2 * half)
; #pragma unroll
;             for (int mm = 0; mm < half; ++mm) { const int ia = m0 + mm, ib = ia + half; const cf a = x[ia], b = x[ib];
;                 x[ia] = cf{a.x + b.x, a.y + b.y}; const cf d{a.x - b.x, a.y - b.y};
;                 x[ib] = cmul(d, twc(ws, (mm << s) * (16 / R))); }
;         ws = cmul(ws, ws); }
; }
; template <int LR> __device__ __forceinline__ void dit_reg(cf (&x)[1 << LR], cf w) {
;     constexpr int R = 1 << LR; cf wsv[LR]; wsv[0] = w;
; #pragma unroll
;     for (int s = 1; s < LR; ++s) wsv[s] = cmul(wsv[s - 1], wsv[s - 1]);
; #pragma unroll
;     for (int s = LR - 1; s >= 0; --s) { const int half = R >> (s + 1);
; #pragma unroll
;         for (int m0 = 0; m0 < R; m0 += 2 * half)
; #pragma unroll
;             for (int mm = 0; mm < half; ++mm) { const int ia = m0 + mm, ib = ia + half; const cf a = x[ia];
;                 const cf b = cmulc(x[ib], twc(wsv[s], (mm << s) * (16 / R)));
;                 x[ia] = cf{a.x + b.x, a.y + b.y}; x[ib] = cf{a.x - b.x, a.y - b.y}; } }
; }
; __device__ __forceinline__ void lds_barrier() { asm volatile("s_waitcnt lgkmcnt(0)\n\ts_barrier" ::: "memory"); }
; template <int LR, bool INV> __device__ __forceinline__ void fft_pass(ldsf2 buf, int base, int stride, int twi) {
;     constexpr int R = 1 << LR; cf x[R];
;     const v2f wv = ((ldsf2)((LAS unsigned char*)buf + 139264))[twi];
; #pragma unroll
;     for (int m = 0; m < R; ++m) { const v2f v = buf[base + m * stride]; x[m] = cf{v.x, v.y}; }
;     const cf w{wv.x, wv.y};
;     if (INV) dit_reg<LR>(x, w); else dif_reg<LR>(x, w);
; #pragma unroll
;     for (int m = 0; m < R; ++m) buf[base + m * stride] = mkv2(x[m].x, x[m].y);
; }
.LBB0_363:
	v_or_b32_e32 v81, s0, v79
	ds_read_b64 v[98:99], v80
	v_lshlrev_b32_e32 v82, 3, v81
	v_ashrrev_i32_e32 v81, 1, v81
	v_add3_u32 v81, v78, v82, v81
	ds_read2_b64 v[82:85], v81 offset1:17
	ds_read2_b64 v[86:89], v81 offset0:34 offset1:51
	ds_read2_b64 v[90:93], v81 offset0:68 offset1:85
	ds_read2_b64 v[94:97], v81 offset0:102 offset1:119
	s_movk_i32 s0, 0x200
	v_or_b32_e32 v126, s0, v79
	v_lshlrev_b32_e32 v130, 3, v126
	v_ashrrev_i32_e32 v126, 1, v126
	v_add3_u32 v126, v78, v130, v126
	ds_read2_b64 v[132:135], v126 offset1:17
	ds_read2_b64 v[136:139], v126 offset0:34 offset1:51
	ds_read2_b64 v[140:143], v126 offset0:68 offset1:85
	ds_read2_b64 v[152:155], v126 offset0:102 offset1:119
	s_waitcnt lgkmcnt(4)
	v_pk_add_f32 v[100:101], v[98:99], v[98:99] op_sel:[0,1] op_sel_hi:[1,0] neg_lo:[0,0] neg_hi:[0,1]
	v_pk_mul_f32 v[106:107], v[98:99], v[98:99] op_sel:[1,1] op_sel_hi:[1,0]
	v_pk_mul_f32 v[102:103], v[100:101], s[16:17] op_sel:[0,0] op_sel_hi:[1,0]
	v_pk_fma_f32 v[106:107], v[98:99], v[98:99], v[106:107] op_sel:[0,0,0] op_sel_hi:[0,1,1] neg_lo:[0,0,1] neg_hi:[0,0,0]
	v_pk_mul_f32 v[104:105], v[100:101], s[16:17] op_sel:[1,0] op_sel_hi:[0,0] neg_lo:[0,0] neg_hi:[1,0]
	s_nop 0
	v_pk_mul_f32 v[108:109], v[106:107], v[106:107] op_sel:[1,1] op_sel_hi:[1,0]
	s_nop 0
	v_pk_fma_f32 v[108:109], v[106:107], v[106:107], v[108:109] op_sel:[0,0,0] op_sel_hi:[0,1,1] neg_lo:[0,0,1] neg_hi:[0,0,0]
	v_pk_add_f32 v[110:111], v[82:83], v[90:91] neg_lo:[0,1] neg_hi:[0,1]
	v_pk_add_f32 v[112:113], v[84:85], v[92:93] neg_lo:[0,1] neg_hi:[0,1]
	v_pk_add_f32 v[114:115], v[86:87], v[94:95] neg_lo:[0,1] neg_hi:[0,1]
	v_pk_add_f32 v[116:117], v[88:89], v[96:97] neg_lo:[0,1] neg_hi:[0,1]
	v_pk_add_f32 v[82:83], v[82:83], v[90:91]
	v_pk_add_f32 v[84:85], v[84:85], v[92:93]
	v_pk_add_f32 v[86:87], v[86:87], v[94:95]
	v_pk_add_f32 v[88:89], v[88:89], v[96:97]
	v_pk_mul_f32 v[90:91], v[110:111], v[98:99] op_sel:[1,1] op_sel_hi:[1,0]
	v_pk_mul_f32 v[92:93], v[112:113], v[102:103] op_sel:[1,1] op_sel_hi:[1,0]
	v_pk_mul_f32 v[94:95], v[114:115], v[98:99] op_sel:[1,0] op_sel_hi:[1,1]
	v_pk_mul_f32 v[96:97], v[116:117], v[104:105] op_sel:[1,1] op_sel_hi:[1,0]
	v_pk_fma_f32 v[90:91], v[110:111], v[98:99], v[90:91] op_sel:[0,0,0] op_sel_hi:[0,1,1] neg_lo:[0,0,1] neg_hi:[0,0,0]
	v_pk_fma_f32 v[92:93], v[112:113], v[102:103], v[92:93] op_sel:[0,0,0] op_sel_hi:[0,1,1] neg_lo:[0,0,1] neg_hi:[0,0,0]
	v_pk_fma_f32 v[94:95], v[114:115], v[98:99], v[94:95] op_sel:[0,1,0] op_sel_hi:[0,0,1] neg_lo:[0,0,0] neg_hi:[0,1,0]
	v_pk_fma_f32 v[96:97], v[116:117], v[104:105], v[96:97] op_sel:[0,0,0] op_sel_hi:[0,1,1] neg_lo:[0,0,1] neg_hi:[0,0,0]
	v_pk_add_f32 v[110:111], v[82:83], v[86:87] neg_lo:[0,1] neg_hi:[0,1]
	v_pk_add_f32 v[112:113], v[84:85], v[88:89] neg_lo:[0,1] neg_hi:[0,1]
	v_pk_add_f32 v[114:115], v[90:91], v[94:95] neg_lo:[0,1] neg_hi:[0,1]
	v_pk_add_f32 v[116:117], v[92:93], v[96:97] neg_lo:[0,1] neg_hi:[0,1]
	v_pk_add_f32 v[82:83], v[82:83], v[86:87]
	v_pk_add_f32 v[84:85], v[84:85], v[88:89]
	v_pk_add_f32 v[90:91], v[90:91], v[94:95]
	v_pk_add_f32 v[92:93], v[92:93], v[96:97]
	v_pk_mul_f32 v[86:87], v[110:111], v[106:107] op_sel:[1,1] op_sel_hi:[1,0]
	v_pk_mul_f32 v[88:89], v[112:113], v[106:107] op_sel:[1,0] op_sel_hi:[1,1]
	v_pk_mul_f32 v[94:95], v[114:115], v[106:107] op_sel:[1,1] op_sel_hi:[1,0]
	v_pk_mul_f32 v[96:97], v[116:117], v[106:107] op_sel:[1,0] op_sel_hi:[1,1]
	v_pk_fma_f32 v[86:87], v[110:111], v[106:107], v[86:87] op_sel:[0,0,0] op_sel_hi:[0,1,1] neg_lo:[0,0,1] neg_hi:[0,0,0]
	v_pk_fma_f32 v[88:89], v[112:113], v[106:107], v[88:89] op_sel:[0,1,0] op_sel_hi:[0,0,1] neg_lo:[0,0,0] neg_hi:[0,1,0]
	v_pk_fma_f32 v[94:95], v[114:115], v[106:107], v[94:95] op_sel:[0,0,0] op_sel_hi:[0,1,1] neg_lo:[0,0,1] neg_hi:[0,0,0]
	v_pk_fma_f32 v[96:97], v[116:117], v[106:107], v[96:97] op_sel:[0,1,0] op_sel_hi:[0,0,1] neg_lo:[0,0,0] neg_hi:[0,1,0]
	v_pk_add_f32 v[110:111], v[82:83], v[84:85] neg_lo:[0,1] neg_hi:[0,1]
	v_pk_add_f32 v[112:113], v[86:87], v[88:89] neg_lo:[0,1] neg_hi:[0,1]
	v_pk_add_f32 v[114:115], v[90:91], v[92:93] neg_lo:[0,1] neg_hi:[0,1]
	v_pk_add_f32 v[116:117], v[94:95], v[96:97] neg_lo:[0,1] neg_hi:[0,1]
	v_pk_add_f32 v[82:83], v[82:83], v[84:85]
	v_pk_add_f32 v[86:87], v[86:87], v[88:89]
	v_pk_add_f32 v[90:91], v[90:91], v[92:93]
	v_pk_add_f32 v[94:95], v[94:95], v[96:97]
	v_pk_mul_f32 v[84:85], v[110:111], v[108:109] op_sel:[1,1] op_sel_hi:[1,0]
	v_pk_mul_f32 v[88:89], v[112:113], v[108:109] op_sel:[1,1] op_sel_hi:[1,0]
	v_pk_mul_f32 v[92:93], v[114:115], v[108:109] op_sel:[1,1] op_sel_hi:[1,0]
	v_pk_mul_f32 v[96:97], v[116:117], v[108:109] op_sel:[1,1] op_sel_hi:[1,0]
	v_pk_fma_f32 v[84:85], v[110:111], v[108:109], v[84:85] op_sel:[0,0,0] op_sel_hi:[0,1,1] neg_lo:[0,0,1] neg_hi:[0,0,0]
	v_pk_fma_f32 v[88:89], v[112:113], v[108:109], v[88:89] op_sel:[0,0,0] op_sel_hi:[0,1,1] neg_lo:[0,0,1] neg_hi:[0,0,0]
	v_pk_fma_f32 v[92:93], v[114:115], v[108:109], v[92:93] op_sel:[0,0,0] op_sel_hi:[0,1,1] neg_lo:[0,0,1] neg_hi:[0,0,0]
	v_pk_fma_f32 v[96:97], v[116:117], v[108:109], v[96:97] op_sel:[0,0,0] op_sel_hi:[0,1,1] neg_lo:[0,0,1] neg_hi:[0,0,0]
	ds_write2_b64 v81, v[82:83], v[84:85] offset1:17
	ds_write2_b64 v81, v[86:87], v[88:89] offset0:34 offset1:51
	ds_write2_b64 v81, v[90:91], v[92:93] offset0:68 offset1:85
	ds_write2_b64 v81, v[94:95], v[96:97] offset0:102 offset1:119
	s_waitcnt lgkmcnt(4)
; #define LAS __attribute__((address_space(3)))
; template <int LR> __device__ __forceinline__ void dif_reg(cf (&x)[1 << LR], cf w) {
;     constexpr int R = 1 << LR; cf ws = w;
; #pragma unroll
;     for (int s = 0; s < LR; ++s) { const int half = R >> (s + 1);
; #pragma unroll
;         for (int m0 = 0; m0 < R; m0 += 2 * half)
; #pragma unroll
;             for (int mm = 0; mm < half; ++mm) { const int ia = m0 + mm, ib = ia + half; const cf a = x[ia], b = x[ib];
;                 x[ia] = cf{a.x + b.x, a.y + b.y}; const cf d{a.x - b.x, a.y - b.y};
;                 x[ib] = cmul(d, twc(ws, (mm << s) * (16 / R))); }
;         ws = cmul(ws, ws); }
; }
; template <int LR> __device__ __forceinline__ void dit_reg(cf (&x)[1 << LR], cf w) {
;     constexpr int R = 1 << LR; cf wsv[LR]; wsv[0] = w;
; #pragma unroll
;     for (int s = 1; s < LR; ++s) wsv[s] = cmul(wsv[s - 1], wsv[s - 1]);
; #pragma unroll
;     for (int s = LR - 1; s >= 0; --s) { const int half = R >> (s + 1);
; #pragma unroll
;         for (int m0 = 0; m0 < R; m0 += 2 * half)
; #pragma unroll
;             for (int mm = 0; mm < half; ++mm) { const int ia = m0 + mm, ib = ia + half; const cf a = x[ia];
;                 const cf b = cmulc(x[ib], twc(wsv[s], (mm << s) * (16 / R)));
;                 x[ia] = cf{a.x + b.x, a.y + b.y}; x[ib] = cf{a.x - b.x, a.y - b.y}; } }
; }
; __device__ __forceinline__ void lds_barrier() { asm volatile("s_waitcnt lgkmcnt(0)\n\ts_barrier" ::: "memory"); }
; template <int LR, bool INV> __device__ __forceinline__ void fft_pass(ldsf2 buf, int base, int stride, int twi) {
;     constexpr int R = 1 << LR; cf x[R];
;     const v2f wv = ((ldsf2)((LAS unsigned char*)buf + 139264))[twi];
; #pragma unroll
;     for (int m = 0; m < R; ++m) { const v2f v = buf[base + m * stride]; x[m] = cf{v.x, v.y}; }
;     const cf w{wv.x, wv.y};
;     if (INV) dit_reg<LR>(x, w); else dif_reg<LR>(x, w);
; #pragma unroll
;     for (int m = 0; m < R; ++m) buf[base + m * stride] = mkv2(x[m].x, x[m].y);
; }
; __device__ __forceinline__ void fft_conv(ldsf2 buf, const LAS unsigned* spec) {
;     fft_fwd_abc(buf);
;     { const int tid = otid(); cf x[16];
; #pragma unroll
;       for (int m = 0; m < 16; ++m) { const v2f v = buf[tid * 17 + m]; x[m] = cf{v.x, v.y}; }
;       dif_reg<4>(x, cf{1.0f, 0.0f});
	v_pk_add_f32 v[156:157], v[132:133], v[140:141] neg_lo:[0,1] neg_hi:[0,1]
	v_pk_add_f32 v[158:159], v[134:135], v[142:143] neg_lo:[0,1] neg_hi:[0,1]
	v_pk_add_f32 v[160:161], v[136:137], v[152:153] neg_lo:[0,1] neg_hi:[0,1]
	v_pk_add_f32 v[162:163], v[138:139], v[154:155] neg_lo:[0,1] neg_hi:[0,1]
	v_pk_add_f32 v[132:133], v[132:133], v[140:141]
	v_pk_add_f32 v[134:135], v[134:135], v[142:143]
	v_pk_add_f32 v[136:137], v[136:137], v[152:153]
	v_pk_add_f32 v[138:139], v[138:139], v[154:155]
	v_pk_mul_f32 v[140:141], v[156:157], v[98:99] op_sel:[1,1] op_sel_hi:[1,0]
	v_pk_mul_f32 v[142:143], v[158:159], v[102:103] op_sel:[1,1] op_sel_hi:[1,0]
	v_pk_mul_f32 v[152:153], v[160:161], v[98:99] op_sel:[1,0] op_sel_hi:[1,1]
	v_pk_mul_f32 v[154:155], v[162:163], v[104:105] op_sel:[1,1] op_sel_hi:[1,0]
	v_pk_fma_f32 v[140:141], v[156:157], v[98:99], v[140:141] op_sel:[0,0,0] op_sel_hi:[0,1,1] neg_lo:[0,0,1] neg_hi:[0,0,0]
	v_pk_fma_f32 v[142:143], v[158:159], v[102:103], v[142:143] op_sel:[0,0,0] op_sel_hi:[0,1,1] neg_lo:[0,0,1] neg_hi:[0,0,0]
	v_pk_fma_f32 v[152:153], v[160:161], v[98:99], v[152:153] op_sel:[0,1,0] op_sel_hi:[0,0,1] neg_lo:[0,0,0] neg_hi:[0,1,0]
	v_pk_fma_f32 v[154:155], v[162:163], v[104:105], v[154:155] op_sel:[0,0,0] op_sel_hi:[0,1,1] neg_lo:[0,0,1] neg_hi:[0,0,0]
	v_pk_add_f32 v[156:157], v[132:133], v[136:137] neg_lo:[0,1] neg_hi:[0,1]
	v_pk_add_f32 v[158:159], v[134:135], v[138:139] neg_lo:[0,1] neg_hi:[0,1]
	v_pk_add_f32 v[160:161], v[140:141], v[152:153] neg_lo:[0,1] neg_hi:[0,1]
	v_pk_add_f32 v[162:163], v[142:143], v[154:155] neg_lo:[0,1] neg_hi:[0,1]
	v_pk_add_f32 v[132:133], v[132:133], v[136:137]
	v_pk_add_f32 v[134:135], v[134:135], v[138:139]
	v_pk_add_f32 v[140:141], v[140:141], v[152:153]
	v_pk_add_f32 v[142:143], v[142:143], v[154:155]
	v_pk_mul_f32 v[136:137], v[156:157], v[106:107] op_sel:[1,1] op_sel_hi:[1,0]
	v_pk_mul_f32 v[138:139], v[158:159], v[106:107] op_sel:[1,0] op_sel_hi:[1,1]
	v_pk_mul_f32 v[152:153], v[160:161], v[106:107] op_sel:[1,1] op_sel_hi:[1,0]
	v_pk_mul_f32 v[154:155], v[162:163], v[106:107] op_sel:[1,0] op_sel_hi:[1,1]
	v_pk_fma_f32 v[136:137], v[156:157], v[106:107], v[136:137] op_sel:[0,0,0] op_sel_hi:[0,1,1] neg_lo:[0,0,1] neg_hi:[0,0,0]
	v_pk_fma_f32 v[138:139], v[158:159], v[106:107], v[138:139] op_sel:[0,1,0] op_sel_hi:[0,0,1] neg_lo:[0,0,0] neg_hi:[0,1,0]
	v_pk_fma_f32 v[152:153], v[160:161], v[106:107], v[152:153] op_sel:[0,0,0] op_sel_hi:[0,1,1] neg_lo:[0,0,1] neg_hi:[0,0,0]
	v_pk_fma_f32 v[154:155], v[162:163], v[106:107], v[154:155] op_sel:[0,1,0] op_sel_hi:[0,0,1] neg_lo:[0,0,0] neg_hi:[0,1,0]
	v_pk_add_f32 v[156:157], v[132:133], v[134:135] neg_lo:[0,1] neg_hi:[0,1]
	v_pk_add_f32 v[158:159], v[136:137], v[138:139] neg_lo:[0,1] neg_hi:[0,1]
	v_pk_add_f32 v[160:161], v[140:141], v[142:143] neg_lo:[0,1] neg_hi:[0,1]
	v_pk_add_f32 v[162:163], v[152:153], v[154:155] neg_lo:[0,1] neg_hi:[0,1]
	v_pk_add_f32 v[132:133], v[132:133], v[134:135]
	v_pk_add_f32 v[136:137], v[136:137], v[138:139]
	v_pk_add_f32 v[140:141], v[140:141], v[142:143]
	v_pk_add_f32 v[152:153], v[152:153], v[154:155]
	v_pk_mul_f32 v[134:135], v[156:157], v[108:109] op_sel:[1,1] op_sel_hi:[1,0]
	v_pk_mul_f32 v[138:139], v[158:159], v[108:109] op_sel:[1,1] op_sel_hi:[1,0]
	v_pk_mul_f32 v[142:143], v[160:161], v[108:109] op_sel:[1,1] op_sel_hi:[1,0]
	v_pk_mul_f32 v[154:155], v[162:163], v[108:109] op_sel:[1,1] op_sel_hi:[1,0]
	v_pk_fma_f32 v[134:135], v[156:157], v[108:109], v[134:135] op_sel:[0,0,0] op_sel_hi:[0,1,1] neg_lo:[0,0,1] neg_hi:[0,0,0]
	v_pk_fma_f32 v[138:139], v[158:159], v[108:109], v[138:139] op_sel:[0,0,0] op_sel_hi:[0,1,1] neg_lo:[0,0,1] neg_hi:[0,0,0]
	v_pk_fma_f32 v[142:143], v[160:161], v[108:109], v[142:143] op_sel:[0,0,0] op_sel_hi:[0,1,1] neg_lo:[0,0,1] neg_hi:[0,0,0]
	v_pk_fma_f32 v[154:155], v[162:163], v[108:109], v[154:155] op_sel:[0,0,0] op_sel_hi:[0,1,1] neg_lo:[0,0,1] neg_hi:[0,0,0]
	ds_write2_b64 v126, v[132:133], v[134:135] offset1:17
	ds_write2_b64 v126, v[136:137], v[138:139] offset0:34 offset1:51
	ds_write2_b64 v126, v[140:141], v[142:143] offset0:68 offset1:85
	ds_write2_b64 v126, v[152:153], v[154:155] offset0:102 offset1:119
	s_mov_b64 s[10:11], 0
	v_mov_b32_e32 v162, v195
	s_movk_i32 s0, 0x88
	s_waitcnt lgkmcnt(0)
	s_mov_b32 s86, s63
	v_mul_lo_u32 v78, v162, s0
	v_add_u32_e32 v151, 0, v78
	ds_read2_b64 v[80:83], v151 offset1:1
	ds_read2_b64 v[84:87], v151 offset0:2 offset1:3
	ds_read2_b64 v[98:101], v151 offset0:4 offset1:5
	ds_read2_b64 v[102:105], v151 offset0:6 offset1:7
	ds_read2_b64 v[106:109], v151 offset0:8 offset1:9
	ds_read2_b64 v[110:113], v151 offset0:10 offset1:11
	ds_read2_b64 v[126:129], v151 offset0:12 offset1:13
	ds_read2_b64 v[134:137], v151 offset0:14 offset1:15
	s_mov_b32 s10, s63
	s_mov_b32 s11, s16
	s_mov_b32 s17, s5
	s_mov_b32 s0, s16
	s_mov_b32 s1, s4
	s_mov_b32 s0, s63
	s_mov_b32 s1, s5
	s_mov_b32 s0, s87
	s_mov_b32 s1, s4
	s_mov_b32 s1, s5
	s_mov_b32 s35, s4
	s_mov_b32 s12, s63
	s_movk_i32 s0, 0x44
	v_mul_lo_u32 v114, v162, s0
	v_add_u32_e32 v114, 0, v114
	v_add_u32_e32 v114, 0x19800, v114
	ds_read2_b32 v[160:161], v114 offset1:1
	ds_read2_b32 v[162:163], v114 offset0:2 offset1:3
	ds_read2_b32 v[164:165], v114 offset0:4 offset1:5
	ds_read2_b32 v[166:167], v114 offset0:6 offset1:7
	ds_read2_b32 v[168:169], v114 offset0:8 offset1:9
	ds_read2_b32 v[142:143], v114 offset0:10 offset1:11
	ds_read2_b32 v[138:139], v114 offset0:12 offset1:13
	ds_read2_b32 v[172:173], v114 offset0:14 offset1:15
	s_mov_b32 s0, s5
	s_mov_b64 s[14:15], -1
	s_mov_b32 s35, s13
	s_mov_b32 s0, s13
	s_waitcnt lgkmcnt(8)
; __device__ __forceinline__ cf twc(cf ws, int k16) { if (k16 == 0) return ws; if (k16 == 4) return cf{ws.y, -ws.x}; return cmul(ws, cf{c16(k16), -s16(k16)}); }
; template <int LR> __device__ __forceinline__ void dif_reg(cf (&x)[1 << LR], cf w) {
;     constexpr int R = 1 << LR; cf ws = w;
; #pragma unroll
;     for (int s = 0; s < LR; ++s) { const int half = R >> (s + 1);
; #pragma unroll
;         for (int m0 = 0; m0 < R; m0 += 2 * half)
; #pragma unroll
;             for (int mm = 0; mm < half; ++mm) { const int ia = m0 + mm, ib = ia + half; const cf a = x[ia], b = x[ib];
;                 x[ia] = cf{a.x + b.x, a.y + b.y}; const cf d{a.x - b.x, a.y - b.y};
;                 x[ib] = cmul(d, twc(ws, (mm << s) * (16 / R))); }
;         ws = cmul(ws, ws); }
; }
	v_pk_add_f32 v[88:89], v[80:81], v[106:107]
	v_pk_add_f32 v[90:91], v[82:83], v[108:109]
	v_pk_add_f32 v[92:93], v[84:85], v[110:111]
	v_pk_add_f32 v[94:95], v[86:87], v[112:113]
	v_pk_add_f32 v[80:81], v[80:81], v[106:107] neg_lo:[0,1] neg_hi:[0,1]
	v_pk_add_f32 v[82:83], v[82:83], v[108:109] neg_lo:[0,1] neg_hi:[0,1]
	v_pk_add_f32 v[84:85], v[84:85], v[110:111] neg_lo:[0,1] neg_hi:[0,1]
	v_pk_add_f32 v[86:87], v[86:87], v[112:113] neg_lo:[0,1] neg_hi:[0,1]
	v_pk_mul_f32 v[108:109], v[82:83], s[4:5] op_sel:[1,1] op_sel_hi:[1,0] neg_lo:[0,1] neg_hi:[0,0]
	v_pk_mul_f32 v[110:111], v[84:85], s[16:17] op_sel:[1,0] op_sel_hi:[1,0] neg_lo:[0,1] neg_hi:[0,0]
	v_pk_mul_f32 v[112:113], v[86:87], s[4:5] op_sel:[1,0] op_sel_hi:[1,1] neg_lo:[0,1] neg_hi:[0,0]
	v_pk_fma_f32 v[108:109], v[82:83], s[4:5], v[108:109] op_sel:[0,0,0] op_sel_hi:[0,1,1] neg_lo:[0,0,1] neg_hi:[0,1,0]
	v_pk_fma_f32 v[110:111], v[84:85], s[16:17], v[110:111] op_sel:[0,0,0] op_sel_hi:[0,0,1] neg_lo:[0,0,1] neg_hi:[0,1,0]
	v_pk_fma_f32 v[112:113], v[86:87], s[4:5], v[112:113] op_sel:[0,1,0] op_sel_hi:[0,0,1] neg_lo:[0,0,1] neg_hi:[0,1,0]
	v_pk_add_f32 v[96:97], v[98:99], v[126:127]
	v_pk_add_f32 v[116:117], v[100:101], v[128:129]
	v_pk_add_f32 v[118:119], v[102:103], v[134:135]
	v_pk_add_f32 v[120:121], v[104:105], v[136:137]
	v_pk_add_f32 v[98:99], v[98:99], v[126:127] op_sel:[1,1] op_sel_hi:[0,0] neg_lo:[0,1] neg_hi:[1,0]
	v_pk_add_f32 v[100:101], v[100:101], v[128:129] neg_lo:[0,1] neg_hi:[0,1]
	v_pk_add_f32 v[102:103], v[102:103], v[134:135] neg_lo:[0,1] neg_hi:[0,1]
	v_pk_add_f32 v[104:105], v[104:105], v[136:137] neg_lo:[0,1] neg_hi:[0,1]
	v_pk_mul_f32 v[128:129], v[100:101], s[4:5] op_sel:[1,0] op_sel_hi:[1,1] neg_lo:[0,1] neg_hi:[0,1]
	v_pk_mul_f32 v[134:135], v[102:103], s[16:17] op_sel:[1,0] op_sel_hi:[1,0] neg_lo:[0,1] neg_hi:[0,1]
	v_pk_mul_f32 v[136:137], v[104:105], s[4:5] op_sel:[1,1] op_sel_hi:[1,0] neg_lo:[0,1] neg_hi:[0,1]
	v_pk_fma_f32 v[128:129], v[100:101], s[4:5], v[128:129] op_sel:[0,1,0] op_sel_hi:[0,0,1] neg_lo:[0,1,1] neg_hi:[0,1,0]
	v_pk_fma_f32 v[134:135], v[102:103], s[16:17], v[134:135] op_sel:[0,0,0] op_sel_hi:[0,0,1] neg_lo:[0,1,1] neg_hi:[0,1,0]
	v_pk_fma_f32 v[136:137], v[104:105], s[4:5], v[136:137] op_sel:[0,0,0] op_sel_hi:[0,1,1] neg_lo:[0,1,1] neg_hi:[0,1,0]
	v_pk_add_f32 v[122:123], v[88:89], v[96:97]
	v_pk_add_f32 v[124:125], v[90:91], v[116:117]
	v_pk_add_f32 v[130:131], v[92:93], v[118:119]
	v_pk_add_f32 v[132:133], v[94:95], v[120:121]
	v_pk_add_f32 v[88:89], v[88:89], v[96:97] neg_lo:[0,1] neg_hi:[0,1]
	v_pk_add_f32 v[90:91], v[90:91], v[116:117] neg_lo:[0,1] neg_hi:[0,1]
	v_pk_add_f32 v[92:93], v[92:93], v[118:119] op_sel:[1,1] op_sel_hi:[0,0] neg_lo:[0,1] neg_hi:[1,0]
	v_pk_add_f32 v[94:95], v[94:95], v[120:121] neg_lo:[0,1] neg_hi:[0,1]
	v_pk_mul_f32 v[116:117], v[90:91], s[16:17] op_sel:[1,0] op_sel_hi:[1,0] neg_lo:[0,1] neg_hi:[0,0]
	v_pk_mul_f32 v[120:121], v[94:95], s[16:17] op_sel:[1,0] op_sel_hi:[1,0] neg_lo:[0,1] neg_hi:[0,1]
	v_pk_fma_f32 v[116:117], v[90:91], s[16:17], v[116:117] op_sel:[0,0,0] op_sel_hi:[0,0,1] neg_lo:[0,0,1] neg_hi:[0,1,0]
	v_pk_fma_f32 v[120:121], v[94:95], s[16:17], v[120:121] op_sel:[0,0,0] op_sel_hi:[0,0,1] neg_lo:[0,1,1] neg_hi:[0,1,0]
	v_pk_add_f32 v[140:141], v[80:81], v[98:99]
	v_pk_add_f32 v[152:153], v[108:109], v[128:129]
	v_pk_add_f32 v[154:155], v[110:111], v[134:135]
	v_pk_add_f32 v[156:157], v[112:113], v[136:137]
	v_pk_add_f32 v[80:81], v[80:81], v[98:99] neg_lo:[0,1] neg_hi:[0,1]
	v_pk_add_f32 v[108:109], v[108:109], v[128:129] neg_lo:[0,1] neg_hi:[0,1]
	v_pk_add_f32 v[110:111], v[110:111], v[134:135] op_sel:[1,1] op_sel_hi:[0,0] neg_lo:[0,1] neg_hi:[1,0]
	v_pk_add_f32 v[112:113], v[112:113], v[136:137] neg_lo:[0,1] neg_hi:[0,1]
	v_pk_mul_f32 v[128:129], v[108:109], s[16:17] op_sel:[1,0] op_sel_hi:[1,0] neg_lo:[0,1] neg_hi:[0,0]
	v_pk_mul_f32 v[136:137], v[112:113], s[16:17] op_sel:[1,0] op_sel_hi:[1,0] neg_lo:[0,1] neg_hi:[0,1]
	v_pk_fma_f32 v[128:129], v[108:109], s[16:17], v[128:129] op_sel:[0,0,0] op_sel_hi:[0,0,1] neg_lo:[0,0,1] neg_hi:[0,1,0]
	v_pk_fma_f32 v[136:137], v[112:113], s[16:17], v[136:137] op_sel:[0,0,0] op_sel_hi:[0,0,1] neg_lo:[0,1,1] neg_hi:[0,1,0]
	v_pk_add_f32 v[158:159], v[122:123], v[130:131]
	v_pk_add_f32 v[170:171], v[124:125], v[132:133]
	v_pk_add_f32 v[106:107], v[88:89], v[92:93]
	v_pk_add_f32 v[82:83], v[116:117], v[120:121]
	v_pk_add_f32 v[122:123], v[122:123], v[130:131] neg_lo:[0,1] neg_hi:[0,1]
	v_pk_add_f32 v[124:125], v[124:125], v[132:133] op_sel:[1,1] op_sel_hi:[0,0] neg_lo:[0,1] neg_hi:[1,0]
	v_pk_add_f32 v[88:89], v[88:89], v[92:93] neg_lo:[0,1] neg_hi:[0,1]
	v_pk_add_f32 v[116:117], v[116:117], v[120:121] op_sel:[1,1] op_sel_hi:[0,0] neg_lo:[0,1] neg_hi:[1,0]
	v_pk_add_f32 v[84:85], v[140:141], v[154:155]
	v_pk_add_f32 v[86:87], v[152:153], v[156:157]
	v_pk_add_f32 v[126:127], v[80:81], v[110:111]
	v_pk_add_f32 v[100:101], v[128:129], v[136:137]
	v_pk_add_f32 v[140:141], v[140:141], v[154:155] neg_lo:[0,1] neg_hi:[0,1]
	v_pk_add_f32 v[152:153], v[152:153], v[156:157] op_sel:[1,1] op_sel_hi:[0,0] neg_lo:[0,1] neg_hi:[1,0]
	v_pk_add_f32 v[80:81], v[80:81], v[110:111] neg_lo:[0,1] neg_hi:[0,1]
	v_pk_add_f32 v[128:129], v[128:129], v[136:137] op_sel:[1,1] op_sel_hi:[0,0] neg_lo:[0,1] neg_hi:[1,0]
	v_pk_add_f32 v[102:103], v[158:159], v[170:171]
	v_pk_add_f32 v[104:105], v[122:123], v[124:125]
	v_pk_add_f32 v[96:97], v[106:107], v[82:83]
	v_pk_add_f32 v[90:91], v[88:89], v[116:117]
	v_pk_add_f32 v[158:159], v[158:159], v[170:171] neg_lo:[0,1] neg_hi:[0,1]
	v_pk_add_f32 v[122:123], v[122:123], v[124:125] neg_lo:[0,1] neg_hi:[0,1]
	v_pk_add_f32 v[106:107], v[106:107], v[82:83] neg_lo:[0,1] neg_hi:[0,1]
	v_pk_add_f32 v[88:89], v[88:89], v[116:117] neg_lo:[0,1] neg_hi:[0,1]
	v_pk_add_f32 v[118:119], v[84:85], v[86:87]
	v_pk_add_f32 v[94:95], v[140:141], v[152:153]
	v_pk_add_f32 v[98:99], v[126:127], v[100:101]
	v_pk_add_f32 v[108:109], v[80:81], v[128:129]
	v_pk_add_f32 v[84:85], v[84:85], v[86:87] neg_lo:[0,1] neg_hi:[0,1]
	v_pk_add_f32 v[140:141], v[140:141], v[152:153] neg_lo:[0,1] neg_hi:[0,1]
	v_pk_add_f32 v[126:127], v[126:127], v[100:101] neg_lo:[0,1] neg_hi:[0,1]
	v_pk_add_f32 v[80:81], v[80:81], v[128:129] neg_lo:[0,1] neg_hi:[0,1]
	s_waitcnt lgkmcnt(0)
; #define LAS __attribute__((address_space(3)))
; __device__ __forceinline__ int otid() { int t = threadIdx.x; asm volatile("" : "+v"(t)); return t; }
; __device__ __forceinline__ void fft_conv(ldsf2 buf, const LAS unsigned* spec) {
;     fft_fwd_abc(buf);
;     { const int tid = otid(); cf x[16];
; #pragma unroll
;       for (int m = 0; m < 16; ++m) { const v2f v = buf[tid * 17 + m]; x[m] = cf{v.x, v.y}; }
;       dif_reg<4>(x, cf{1.0f, 0.0f});
; #pragma unroll
;       for (int m = 0; m < 16; ++m) { const h2_t hv = __builtin_bit_cast(h2_t, spec[tid * 17 + m]); x[m] = cmul(x[m], cf{(float)hv.x, (float)hv.y}); }
;       dit_reg<4>(x, cf{1.0f, 0.0f});
; #pragma unroll
	v_cvt_f32_f16_e32 v134, v160
	v_cvt_f32_f16_e32 v130, v161
	v_cvt_f32_f16_e32 v92, v162
	v_cvt_f32_f16_e32 v154, v163
	v_cvt_f32_f16_sdwa v135, v160 dst_sel:DWORD dst_unused:UNUSED_PAD src0_sel:WORD_1
	v_cvt_f32_f16_sdwa v131, v161 dst_sel:DWORD dst_unused:UNUSED_PAD src0_sel:WORD_1
	v_cvt_f32_f16_sdwa v93, v162 dst_sel:DWORD dst_unused:UNUSED_PAD src0_sel:WORD_1
	v_cvt_f32_f16_sdwa v155, v163 dst_sel:DWORD dst_unused:UNUSED_PAD src0_sel:WORD_1
	v_pk_mul_f32 v[112:113], v[102:103], v[134:135] op_sel:[1,1] op_sel_hi:[1,0]
	v_pk_mul_f32 v[132:133], v[158:159], v[130:131] op_sel:[1,1] op_sel_hi:[1,0]
	v_pk_mul_f32 v[120:121], v[104:105], v[92:93] op_sel:[1,1] op_sel_hi:[1,0]
	v_pk_mul_f32 v[156:157], v[122:123], v[154:155] op_sel:[1,1] op_sel_hi:[1,0]
	v_pk_fma_f32 v[134:135], v[102:103], v[134:135], v[112:113] op_sel:[0,0,0] op_sel_hi:[0,1,1] neg_lo:[0,0,1] neg_hi:[0,0,0]
	v_pk_fma_f32 v[130:131], v[158:159], v[130:131], v[132:133] op_sel:[0,0,0] op_sel_hi:[0,1,1] neg_lo:[0,0,1] neg_hi:[0,0,0]
	v_pk_fma_f32 v[92:93], v[104:105], v[92:93], v[120:121] op_sel:[0,0,0] op_sel_hi:[0,1,1] neg_lo:[0,0,1] neg_hi:[0,0,0]
	v_pk_fma_f32 v[154:155], v[122:123], v[154:155], v[156:157] op_sel:[0,0,0] op_sel_hi:[0,1,1] neg_lo:[0,0,1] neg_hi:[0,0,0]
	v_cvt_f32_f16_e32 v110, v164
	v_cvt_f32_f16_e32 v170, v165
	v_cvt_f32_f16_e32 v82, v166
	v_cvt_f32_f16_e32 v86, v167
	v_cvt_f32_f16_sdwa v111, v164 dst_sel:DWORD dst_unused:UNUSED_PAD src0_sel:WORD_1
	v_cvt_f32_f16_sdwa v171, v165 dst_sel:DWORD dst_unused:UNUSED_PAD src0_sel:WORD_1
	v_cvt_f32_f16_sdwa v83, v166 dst_sel:DWORD dst_unused:UNUSED_PAD src0_sel:WORD_1
	v_cvt_f32_f16_sdwa v87, v167 dst_sel:DWORD dst_unused:UNUSED_PAD src0_sel:WORD_1
	v_pk_mul_f32 v[136:137], v[96:97], v[110:111] op_sel:[1,1] op_sel_hi:[1,0]
	v_pk_mul_f32 v[124:125], v[106:107], v[170:171] op_sel:[1,1] op_sel_hi:[1,0]
	v_pk_mul_f32 v[116:117], v[90:91], v[82:83] op_sel:[1,1] op_sel_hi:[1,0]
	v_pk_mul_f32 v[152:153], v[88:89], v[86:87] op_sel:[1,1] op_sel_hi:[1,0]
	v_pk_fma_f32 v[110:111], v[96:97], v[110:111], v[136:137] op_sel:[0,0,0] op_sel_hi:[0,1,1] neg_lo:[0,0,1] neg_hi:[0,0,0]
	v_pk_fma_f32 v[170:171], v[106:107], v[170:171], v[124:125] op_sel:[0,0,0] op_sel_hi:[0,1,1] neg_lo:[0,0,1] neg_hi:[0,0,0]
	v_pk_fma_f32 v[82:83], v[90:91], v[82:83], v[116:117] op_sel:[0,0,0] op_sel_hi:[0,1,1] neg_lo:[0,0,1] neg_hi:[0,0,0]
	v_pk_fma_f32 v[86:87], v[88:89], v[86:87], v[152:153] op_sel:[0,0,0] op_sel_hi:[0,1,1] neg_lo:[0,0,1] neg_hi:[0,0,0]
	v_cvt_f32_f16_e32 v100, v168
	v_cvt_f32_f16_e32 v112, v169
	v_cvt_f32_f16_e32 v132, v142
	v_cvt_f32_f16_e32 v120, v143
	v_cvt_f32_f16_sdwa v101, v168 dst_sel:DWORD dst_unused:UNUSED_PAD src0_sel:WORD_1
	v_cvt_f32_f16_sdwa v113, v169 dst_sel:DWORD dst_unused:UNUSED_PAD src0_sel:WORD_1
	v_cvt_f32_f16_sdwa v133, v142 dst_sel:DWORD dst_unused:UNUSED_PAD src0_sel:WORD_1
	v_cvt_f32_f16_sdwa v121, v143 dst_sel:DWORD dst_unused:UNUSED_PAD src0_sel:WORD_1
	v_pk_mul_f32 v[128:129], v[118:119], v[100:101] op_sel:[1,1] op_sel_hi:[1,0]
	v_pk_mul_f32 v[102:103], v[84:85], v[112:113] op_sel:[1,1] op_sel_hi:[1,0]
	v_pk_mul_f32 v[158:159], v[94:95], v[132:133] op_sel:[1,1] op_sel_hi:[1,0]
	v_pk_mul_f32 v[104:105], v[140:141], v[120:121] op_sel:[1,1] op_sel_hi:[1,0]
	v_pk_fma_f32 v[100:101], v[118:119], v[100:101], v[128:129] op_sel:[0,0,0] op_sel_hi:[0,1,1] neg_lo:[0,0,1] neg_hi:[0,0,0]
	v_pk_fma_f32 v[112:113], v[84:85], v[112:113], v[102:103] op_sel:[0,0,0] op_sel_hi:[0,1,1] neg_lo:[0,0,1] neg_hi:[0,0,0]
	v_pk_fma_f32 v[132:133], v[94:95], v[132:133], v[158:159] op_sel:[0,0,0] op_sel_hi:[0,1,1] neg_lo:[0,0,1] neg_hi:[0,0,0]
	v_pk_fma_f32 v[120:121], v[140:141], v[120:121], v[104:105] op_sel:[0,0,0] op_sel_hi:[0,1,1] neg_lo:[0,0,1] neg_hi:[0,0,0]
	v_cvt_f32_f16_e32 v156, v138
	v_cvt_f32_f16_e32 v136, v139
	v_cvt_f32_f16_e32 v124, v172
	v_cvt_f32_f16_e32 v116, v173
	v_cvt_f32_f16_sdwa v157, v138 dst_sel:DWORD dst_unused:UNUSED_PAD src0_sel:WORD_1
	v_cvt_f32_f16_sdwa v137, v139 dst_sel:DWORD dst_unused:UNUSED_PAD src0_sel:WORD_1
	v_cvt_f32_f16_sdwa v125, v172 dst_sel:DWORD dst_unused:UNUSED_PAD src0_sel:WORD_1
	v_cvt_f32_f16_sdwa v117, v173 dst_sel:DWORD dst_unused:UNUSED_PAD src0_sel:WORD_1
	v_pk_mul_f32 v[122:123], v[98:99], v[156:157] op_sel:[1,1] op_sel_hi:[1,0]
	v_pk_mul_f32 v[96:97], v[126:127], v[136:137] op_sel:[1,1] op_sel_hi:[1,0]
	v_pk_mul_f32 v[106:107], v[108:109], v[124:125] op_sel:[1,1] op_sel_hi:[1,0]
	v_pk_mul_f32 v[90:91], v[80:81], v[116:117] op_sel:[1,1] op_sel_hi:[1,0]
	v_pk_fma_f32 v[156:157], v[98:99], v[156:157], v[122:123] op_sel:[0,0,0] op_sel_hi:[0,1,1] neg_lo:[0,0,1] neg_hi:[0,0,0]
	v_pk_fma_f32 v[136:137], v[126:127], v[136:137], v[96:97] op_sel:[0,0,0] op_sel_hi:[0,1,1] neg_lo:[0,0,1] neg_hi:[0,0,0]
	v_pk_fma_f32 v[124:125], v[108:109], v[124:125], v[106:107] op_sel:[0,0,0] op_sel_hi:[0,1,1] neg_lo:[0,0,1] neg_hi:[0,0,0]
	v_pk_fma_f32 v[116:117], v[80:81], v[116:117], v[90:91] op_sel:[0,0,0] op_sel_hi:[0,1,1] neg_lo:[0,0,1] neg_hi:[0,0,0]
	v_pk_add_f32 v[152:153], v[134:135], v[130:131]
	v_pk_add_f32 v[88:89], v[92:93], v[154:155]
	v_pk_add_f32 v[128:129], v[110:111], v[170:171]
	v_pk_add_f32 v[118:119], v[82:83], v[86:87]
	v_pk_add_f32 v[134:135], v[134:135], v[130:131] neg_lo:[0,1] neg_hi:[0,1]
	v_pk_add_f32 v[92:93], v[92:93], v[154:155] neg_lo:[0,1] neg_hi:[0,1]
	v_pk_add_f32 v[110:111], v[110:111], v[170:171] neg_lo:[0,1] neg_hi:[0,1]
	v_pk_add_f32 v[82:83], v[82:83], v[86:87] neg_lo:[0,1] neg_hi:[0,1]
	v_pk_add_f32 v[102:103], v[100:101], v[112:113]
	v_pk_add_f32 v[84:85], v[132:133], v[120:121]
	v_pk_add_f32 v[158:159], v[156:157], v[136:137]
	v_pk_add_f32 v[94:95], v[124:125], v[116:117]
; __device__ __forceinline__ cf twc(cf ws, int k16) { if (k16 == 0) return ws; if (k16 == 4) return cf{ws.y, -ws.x}; return cmul(ws, cf{c16(k16), -s16(k16)}); }
; __device__ __forceinline__ void wave_lds_fence() { asm volatile("s_waitcnt lgkmcnt(0)" ::: "memory"); }
; template <int LR> __device__ __forceinline__ void dit_reg(cf (&x)[1 << LR], cf w) {
;     constexpr int R = 1 << LR; cf wsv[LR]; wsv[0] = w;
; #pragma unroll
;     for (int s = 1; s < LR; ++s) wsv[s] = cmul(wsv[s - 1], wsv[s - 1]);
; #pragma unroll
;     for (int s = LR - 1; s >= 0; --s) { const int half = R >> (s + 1);
; #pragma unroll
;         for (int m0 = 0; m0 < R; m0 += 2 * half)
; #pragma unroll
;             for (int mm = 0; mm < half; ++mm) { const int ia = m0 + mm, ib = ia + half; const cf a = x[ia];
;                 const cf b = cmulc(x[ib], twc(wsv[s], (mm << s) * (16 / R)));
;                 x[ia] = cf{a.x + b.x, a.y + b.y}; x[ib] = cf{a.x - b.x, a.y - b.y}; } }
; }
; __device__ __forceinline__ void fft_conv(ldsf2 buf, const LAS unsigned* spec) {
;     ...
;       dit_reg<4>(x, cf{1.0f, 0.0f});
; #pragma unroll
;       for (int m = 0; m < 16; ++m) buf[tid * 17 + m] = mkv2(x[m].x, x[m].y); }
;     wave_lds_fence();
	v_pk_add_f32 v[100:101], v[100:101], v[112:113] neg_lo:[0,1] neg_hi:[0,1]
	v_pk_add_f32 v[132:133], v[132:133], v[120:121] neg_lo:[0,1] neg_hi:[0,1]
	v_pk_add_f32 v[156:157], v[156:157], v[136:137] neg_lo:[0,1] neg_hi:[0,1]
	v_pk_add_f32 v[124:125], v[124:125], v[116:117] neg_lo:[0,1] neg_hi:[0,1]
	v_pk_add_f32 v[104:105], v[152:153], v[88:89]
	v_pk_add_f32 v[140:141], v[134:135], v[92:93] op_sel:[0,1] op_sel_hi:[1,0] neg_lo:[0,1] neg_hi:[0,0]
	v_pk_add_f32 v[122:123], v[128:129], v[118:119]
	v_pk_add_f32 v[98:99], v[110:111], v[82:83] op_sel:[0,1] op_sel_hi:[1,0] neg_lo:[0,1] neg_hi:[0,0]
	v_pk_add_f32 v[152:153], v[152:153], v[88:89] neg_lo:[0,1] neg_hi:[0,1]
	v_pk_add_f32 v[134:135], v[134:135], v[92:93] op_sel:[0,1] op_sel_hi:[1,0] neg_lo:[0,0] neg_hi:[0,1]
	v_pk_add_f32 v[128:129], v[128:129], v[118:119] neg_lo:[0,1] neg_hi:[0,1]
	v_pk_add_f32 v[110:111], v[110:111], v[82:83] op_sel:[0,1] op_sel_hi:[1,0] neg_lo:[0,0] neg_hi:[0,1]
	v_pk_add_f32 v[96:97], v[102:103], v[84:85]
	v_pk_add_f32 v[126:127], v[100:101], v[132:133] op_sel:[0,1] op_sel_hi:[1,0] neg_lo:[0,1] neg_hi:[0,0]
	v_pk_add_f32 v[106:107], v[158:159], v[94:95]
	v_pk_add_f32 v[108:109], v[156:157], v[124:125] op_sel:[0,1] op_sel_hi:[1,0] neg_lo:[0,1] neg_hi:[0,0]
	v_pk_add_f32 v[102:103], v[102:103], v[84:85] neg_lo:[0,1] neg_hi:[0,1]
	v_pk_add_f32 v[100:101], v[100:101], v[132:133] op_sel:[0,1] op_sel_hi:[1,0] neg_lo:[0,0] neg_hi:[0,1]
	v_pk_add_f32 v[158:159], v[158:159], v[94:95] neg_lo:[0,1] neg_hi:[0,1]
	v_pk_add_f32 v[156:157], v[156:157], v[124:125] op_sel:[0,1] op_sel_hi:[1,0] neg_lo:[0,0] neg_hi:[0,1]
	v_pk_add_f32 v[90:91], v[104:105], v[122:123]
	v_pk_mul_f32 v[80:81], v[98:99], s[16:17] op_sel:[1,0] op_sel_hi:[1,0] neg_lo:[0,1] neg_hi:[0,0]
	v_pk_add_f32 v[130:131], v[152:153], v[128:129] op_sel:[0,1] op_sel_hi:[1,0] neg_lo:[0,1] neg_hi:[0,0]
	v_pk_mul_f32 v[154:155], v[110:111], s[16:17] op_sel:[1,0] op_sel_hi:[1,0] neg_lo:[0,1] neg_hi:[0,1]
	v_pk_add_f32 v[104:105], v[104:105], v[122:123] neg_lo:[0,1] neg_hi:[0,1]
	v_pk_fma_f32 v[80:81], v[98:99], s[16:17], v[80:81] op_sel:[0,0,0] op_sel_hi:[0,0,1] neg_lo:[0,0,0] neg_hi:[0,0,0]
	v_pk_add_f32 v[152:153], v[152:153], v[128:129] op_sel:[0,1] op_sel_hi:[1,0] neg_lo:[0,0] neg_hi:[0,1]
	v_pk_fma_f32 v[154:155], v[110:111], s[16:17], v[154:155] op_sel:[0,0,0] op_sel_hi:[0,0,1] neg_lo:[0,1,0] neg_hi:[0,0,0]
	v_pk_add_f32 v[98:99], v[140:141], v[80:81] neg_lo:[0,1] neg_hi:[0,1]
	v_pk_add_f32 v[110:111], v[134:135], v[154:155] neg_lo:[0,1] neg_hi:[0,1]
	v_pk_add_f32 v[140:141], v[140:141], v[80:81]
	v_pk_add_f32 v[134:135], v[134:135], v[154:155]
	v_pk_add_f32 v[170:171], v[96:97], v[106:107]
	v_pk_mul_f32 v[86:87], v[108:109], s[16:17] op_sel:[1,0] op_sel_hi:[1,0] neg_lo:[0,1] neg_hi:[0,0]
	v_pk_add_f32 v[112:113], v[102:103], v[158:159] op_sel:[0,1] op_sel_hi:[1,0] neg_lo:[0,1] neg_hi:[0,0]
	v_pk_mul_f32 v[120:121], v[156:157], s[16:17] op_sel:[1,0] op_sel_hi:[1,0] neg_lo:[0,1] neg_hi:[0,1]
	v_pk_add_f32 v[96:97], v[96:97], v[106:107] neg_lo:[0,1] neg_hi:[0,1]
	v_pk_fma_f32 v[86:87], v[108:109], s[16:17], v[86:87] op_sel:[0,0,0] op_sel_hi:[0,0,1] neg_lo:[0,0,0] neg_hi:[0,0,0]
	v_pk_add_f32 v[102:103], v[102:103], v[158:159] op_sel:[0,1] op_sel_hi:[1,0] neg_lo:[0,0] neg_hi:[0,1]
	v_pk_fma_f32 v[120:121], v[156:157], s[16:17], v[120:121] op_sel:[0,0,0] op_sel_hi:[0,0,1] neg_lo:[0,1,0] neg_hi:[0,0,0]
	v_pk_add_f32 v[108:109], v[126:127], v[86:87] neg_lo:[0,1] neg_hi:[0,1]
	v_pk_add_f32 v[156:157], v[100:101], v[120:121] neg_lo:[0,1] neg_hi:[0,1]
	v_pk_add_f32 v[126:127], v[126:127], v[86:87]
	v_pk_add_f32 v[100:101], v[100:101], v[120:121]
	v_pk_add_f32 v[136:137], v[90:91], v[170:171]
	v_pk_mul_f32 v[116:117], v[126:127], s[4:5] op_sel:[1,1] op_sel_hi:[1,0] neg_lo:[0,1] neg_hi:[0,0]
	v_pk_mul_f32 v[88:89], v[112:113], s[16:17] op_sel:[1,0] op_sel_hi:[1,0] neg_lo:[0,1] neg_hi:[0,0]
	v_pk_mul_f32 v[92:93], v[100:101], s[4:5] op_sel:[1,0] op_sel_hi:[1,1] neg_lo:[0,1] neg_hi:[0,0]
	v_pk_add_f32 v[90:91], v[90:91], v[170:171] neg_lo:[0,1] neg_hi:[0,1]
	v_pk_fma_f32 v[116:117], v[126:127], s[4:5], v[116:117] op_sel:[0,0,0] op_sel_hi:[0,1,1] neg_lo:[0,0,0] neg_hi:[0,0,0]
	v_pk_fma_f32 v[88:89], v[112:113], s[16:17], v[88:89] op_sel:[0,0,0] op_sel_hi:[0,0,1] neg_lo:[0,0,0] neg_hi:[0,0,0]
	v_pk_fma_f32 v[92:93], v[100:101], s[4:5], v[92:93] op_sel:[0,1,0] op_sel_hi:[0,0,1] neg_lo:[0,0,0] neg_hi:[0,0,0]
	v_pk_add_f32 v[126:127], v[140:141], v[116:117] neg_lo:[0,1] neg_hi:[0,1]
	v_pk_add_f32 v[112:113], v[130:131], v[88:89] neg_lo:[0,1] neg_hi:[0,1]
	v_pk_add_f32 v[100:101], v[134:135], v[92:93] neg_lo:[0,1] neg_hi:[0,1]
	v_pk_add_f32 v[140:141], v[140:141], v[116:117]
	v_pk_add_f32 v[130:131], v[130:131], v[88:89]
	v_pk_add_f32 v[134:135], v[134:135], v[92:93]
	v_pk_add_f32 v[118:119], v[104:105], v[96:97] op_sel:[0,1] op_sel_hi:[1,0] neg_lo:[0,1] neg_hi:[0,0]
	v_pk_mul_f32 v[82:83], v[108:109], s[4:5] op_sel:[1,0] op_sel_hi:[1,1] neg_lo:[0,1] neg_hi:[0,1]
	v_pk_mul_f32 v[84:85], v[102:103], s[16:17] op_sel:[1,0] op_sel_hi:[1,0] neg_lo:[0,1] neg_hi:[0,1]
	v_pk_mul_f32 v[132:133], v[156:157], s[4:5] op_sel:[1,1] op_sel_hi:[1,0] neg_lo:[0,1] neg_hi:[0,1]
	v_pk_add_f32 v[104:105], v[104:105], v[96:97] op_sel:[0,1] op_sel_hi:[1,0] neg_lo:[0,0] neg_hi:[0,1]
	v_pk_fma_f32 v[82:83], v[108:109], s[4:5], v[82:83] op_sel:[0,1,0] op_sel_hi:[0,0,1] neg_lo:[0,1,0] neg_hi:[0,0,0]
	v_pk_fma_f32 v[84:85], v[102:103], s[16:17], v[84:85] op_sel:[0,0,0] op_sel_hi:[0,0,1] neg_lo:[0,1,0] neg_hi:[0,0,0]
	v_pk_fma_f32 v[132:133], v[156:157], s[4:5], v[132:133] op_sel:[0,0,0] op_sel_hi:[0,1,1] neg_lo:[0,1,0] neg_hi:[0,0,0]
	v_pk_add_f32 v[108:109], v[98:99], v[82:83] neg_lo:[0,1] neg_hi:[0,1]
	v_pk_add_f32 v[102:103], v[152:153], v[84:85] neg_lo:[0,1] neg_hi:[0,1]
	v_pk_add_f32 v[156:157], v[110:111], v[132:133] neg_lo:[0,1] neg_hi:[0,1]
	v_pk_add_f32 v[98:99], v[98:99], v[82:83]
	v_pk_add_f32 v[152:153], v[152:153], v[84:85]
	v_pk_add_f32 v[110:111], v[110:111], v[132:133]
	ds_write2_b64 v151, v[136:137], v[140:141] offset1:1
	ds_write2_b64 v151, v[130:131], v[134:135] offset0:2 offset1:3
	ds_write2_b64 v151, v[118:119], v[98:99] offset0:4 offset1:5
	ds_write2_b64 v151, v[152:153], v[110:111] offset0:6 offset1:7
	ds_write2_b64 v151, v[90:91], v[126:127] offset0:8 offset1:9
	ds_write2_b64 v151, v[112:113], v[100:101] offset0:10 offset1:11
	ds_write2_b64 v151, v[104:105], v[108:109] offset0:12 offset1:13
	ds_write2_b64 v151, v[102:103], v[156:157] offset0:14 offset1:15
	v_mov_b32_e32 v78, v195
	s_waitcnt lgkmcnt(0)
	s_mov_b32 s0, 0
	v_and_b32_e32 v81, 15, v78
	v_lshlrev_b32_e32 v80, 4, v78
	v_lshlrev_b32_e32 v83, 9, v81
	v_and_b32_e32 v80, 0xfffffc00, v80
	v_lshlrev_b32_e32 v82, 3, v78
	v_add_u32_e32 v83, 0, v83
	v_and_b32_e32 v79, 63, v78
	v_lshl_add_u32 v81, v81, 3, 0
	v_and_or_b32 v82, v82, s90, v80
	v_add_u32_e32 v83, 0x22000, v83
; #define LAS __attribute__((address_space(3)))
; __device__ __forceinline__ cf twc(cf ws, int k16) { if (k16 == 0) return ws; if (k16 == 4) return cf{ws.y, -ws.x}; return cmul(ws, cf{c16(k16), -s16(k16)}); }
; template <int LR> __device__ __forceinline__ void dit_reg(cf (&x)[1 << LR], cf w) {
;     constexpr int R = 1 << LR; cf wsv[LR]; wsv[0] = w;
; #pragma unroll
;     for (int s = 1; s < LR; ++s) wsv[s] = cmul(wsv[s - 1], wsv[s - 1]);
; #pragma unroll
;     for (int s = LR - 1; s >= 0; --s) { const int half = R >> (s + 1);
; #pragma unroll
;         for (int m0 = 0; m0 < R; m0 += 2 * half)
; #pragma unroll
;             for (int mm = 0; mm < half; ++mm) { const int ia = m0 + mm, ib = ia + half; const cf a = x[ia];
;                 const cf b = cmulc(x[ib], twc(wsv[s], (mm << s) * (16 / R)));
;                 x[ia] = cf{a.x + b.x, a.y + b.y}; x[ib] = cf{a.x - b.x, a.y - b.y}; } }
; }
; __device__ __forceinline__ void lds_barrier() { asm volatile("s_waitcnt lgkmcnt(0)\n\ts_barrier" ::: "memory"); }
; template <int LR, bool INV> __device__ __forceinline__ void fft_pass(ldsf2 buf, int base, int stride, int twi) {
;     constexpr int R = 1 << LR; cf x[R];
;     const v2f wv = ((ldsf2)((LAS unsigned char*)buf + 139264))[twi];
; #pragma unroll
;     for (int m = 0; m < R; ++m) { const v2f v = buf[base + m * stride]; x[m] = cf{v.x, v.y}; }
;     const cf w{wv.x, wv.y};
;     if (INV) dit_reg<LR>(x, w); else dif_reg<LR>(x, w);
; #pragma unroll
;     for (int m = 0; m < R; ++m) buf[base + m * stride] = mkv2(x[m].x, x[m].y);
; }
.LBB0_365:
	ds_read_b64 v[100:101], v83
	v_or_b32_e32 v84, s0, v82
	v_lshlrev_b32_e32 v85, 3, v84
	v_ashrrev_i32_e32 v84, 1, v84
	v_add3_u32 v130, v81, v85, v84
	ds_read2_b64 v[84:87], v130 offset1:17
	ds_read2_b64 v[88:91], v130 offset0:34 offset1:51
	ds_read2_b64 v[92:95], v130 offset0:68 offset1:85
	ds_read2_b64 v[96:99], v130 offset0:102 offset1:119
	s_movk_i32 s0, 0x200
	v_or_b32_e32 v134, s0, v82
	v_lshlrev_b32_e32 v136, 3, v134
	v_ashrrev_i32_e32 v134, 1, v134
	v_add3_u32 v138, v81, v136, v134
	ds_read2_b64 v[140:143], v138 offset1:17
	ds_read2_b64 v[152:155], v138 offset0:34 offset1:51
	ds_read2_b64 v[156:159], v138 offset0:68 offset1:85
	ds_read2_b64 v[160:163], v138 offset0:102 offset1:119
	s_waitcnt lgkmcnt(4)
	v_pk_add_f32 v[102:103], v[100:101], v[100:101] op_sel:[0,1] op_sel_hi:[1,0] neg_lo:[0,0] neg_hi:[0,1]
	v_pk_mul_f32 v[108:109], v[100:101], v[100:101] op_sel:[1,1] op_sel_hi:[1,0]
	v_pk_mul_f32 v[104:105], v[102:103], s[16:17] op_sel:[0,0] op_sel_hi:[1,0]
	v_pk_fma_f32 v[108:109], v[100:101], v[100:101], v[108:109] op_sel:[0,0,0] op_sel_hi:[0,1,1] neg_lo:[0,0,1] neg_hi:[0,0,0]
	v_pk_mul_f32 v[106:107], v[102:103], s[16:17] op_sel:[1,0] op_sel_hi:[0,0] neg_lo:[0,0] neg_hi:[1,0]
	s_nop 0
	v_pk_mul_f32 v[110:111], v[108:109], v[108:109] op_sel:[1,1] op_sel_hi:[1,0]
	s_nop 0
	v_pk_fma_f32 v[110:111], v[108:109], v[108:109], v[110:111] op_sel:[0,0,0] op_sel_hi:[0,1,1] neg_lo:[0,0,1] neg_hi:[0,0,0]
	v_pk_mul_f32 v[112:113], v[86:87], v[110:111] op_sel:[1,1] op_sel_hi:[1,0]
	v_pk_mul_f32 v[114:115], v[90:91], v[110:111] op_sel:[1,1] op_sel_hi:[1,0]
	v_pk_mul_f32 v[116:117], v[94:95], v[110:111] op_sel:[1,1] op_sel_hi:[1,0]
	v_pk_mul_f32 v[118:119], v[98:99], v[110:111] op_sel:[1,1] op_sel_hi:[1,0]
	v_pk_fma_f32 v[112:113], v[86:87], v[110:111], v[112:113] op_sel:[0,0,0] op_sel_hi:[0,1,1] neg_lo:[0,0,0] neg_hi:[0,1,0]
	v_pk_fma_f32 v[114:115], v[90:91], v[110:111], v[114:115] op_sel:[0,0,0] op_sel_hi:[0,1,1] neg_lo:[0,0,0] neg_hi:[0,1,0]
	v_pk_fma_f32 v[116:117], v[94:95], v[110:111], v[116:117] op_sel:[0,0,0] op_sel_hi:[0,1,1] neg_lo:[0,0,0] neg_hi:[0,1,0]
	v_pk_fma_f32 v[118:119], v[98:99], v[110:111], v[118:119] op_sel:[0,0,0] op_sel_hi:[0,1,1] neg_lo:[0,0,0] neg_hi:[0,1,0]
	v_pk_add_f32 v[86:87], v[84:85], v[112:113] neg_lo:[0,1] neg_hi:[0,1]
	v_pk_add_f32 v[90:91], v[88:89], v[114:115] neg_lo:[0,1] neg_hi:[0,1]
	v_pk_add_f32 v[94:95], v[92:93], v[116:117] neg_lo:[0,1] neg_hi:[0,1]
	v_pk_add_f32 v[98:99], v[96:97], v[118:119] neg_lo:[0,1] neg_hi:[0,1]
	v_pk_add_f32 v[84:85], v[84:85], v[112:113]
	v_pk_add_f32 v[88:89], v[88:89], v[114:115]
	v_pk_add_f32 v[92:93], v[92:93], v[116:117]
	v_pk_add_f32 v[96:97], v[96:97], v[118:119]
	v_pk_mul_f32 v[112:113], v[88:89], v[108:109] op_sel:[1,1] op_sel_hi:[1,0]
	v_pk_mul_f32 v[114:115], v[90:91], v[108:109] op_sel:[1,0] op_sel_hi:[1,1]
	v_pk_mul_f32 v[116:117], v[96:97], v[108:109] op_sel:[1,1] op_sel_hi:[1,0]
	v_pk_mul_f32 v[118:119], v[98:99], v[108:109] op_sel:[1,0] op_sel_hi:[1,1]
	v_pk_fma_f32 v[112:113], v[88:89], v[108:109], v[112:113] op_sel:[0,0,0] op_sel_hi:[0,1,1] neg_lo:[0,0,0] neg_hi:[0,1,0]
	v_pk_fma_f32 v[114:115], v[90:91], v[108:109], v[114:115] op_sel:[0,1,0] op_sel_hi:[0,0,1] neg_lo:[0,0,1] neg_hi:[0,0,0]
	v_pk_fma_f32 v[116:117], v[96:97], v[108:109], v[116:117] op_sel:[0,0,0] op_sel_hi:[0,1,1] neg_lo:[0,0,0] neg_hi:[0,1,0]
	v_pk_fma_f32 v[118:119], v[98:99], v[108:109], v[118:119] op_sel:[0,1,0] op_sel_hi:[0,0,1] neg_lo:[0,0,1] neg_hi:[0,0,0]
	v_pk_add_f32 v[88:89], v[84:85], v[112:113] neg_lo:[0,1] neg_hi:[0,1]
	v_pk_add_f32 v[90:91], v[86:87], v[114:115] neg_lo:[0,1] neg_hi:[0,1]
	v_pk_add_f32 v[96:97], v[92:93], v[116:117] neg_lo:[0,1] neg_hi:[0,1]
	v_pk_add_f32 v[98:99], v[94:95], v[118:119] neg_lo:[0,1] neg_hi:[0,1]
	v_pk_add_f32 v[84:85], v[84:85], v[112:113]
	v_pk_add_f32 v[86:87], v[86:87], v[114:115]
	v_pk_add_f32 v[92:93], v[92:93], v[116:117]
	v_pk_add_f32 v[94:95], v[94:95], v[118:119]
	v_pk_mul_f32 v[112:113], v[92:93], v[100:101] op_sel:[1,1] op_sel_hi:[1,0]
	v_pk_mul_f32 v[114:115], v[94:95], v[104:105] op_sel:[1,1] op_sel_hi:[1,0]
	v_pk_mul_f32 v[116:117], v[96:97], v[100:101] op_sel:[1,0] op_sel_hi:[1,1]
	v_pk_mul_f32 v[118:119], v[98:99], v[106:107] op_sel:[1,1] op_sel_hi:[1,0]
	v_pk_fma_f32 v[112:113], v[92:93], v[100:101], v[112:113] op_sel:[0,0,0] op_sel_hi:[0,1,1] neg_lo:[0,0,0] neg_hi:[0,1,0]
	v_pk_fma_f32 v[114:115], v[94:95], v[104:105], v[114:115] op_sel:[0,0,0] op_sel_hi:[0,1,1] neg_lo:[0,0,0] neg_hi:[0,1,0]
	v_pk_fma_f32 v[116:117], v[96:97], v[100:101], v[116:117] op_sel:[0,1,0] op_sel_hi:[0,0,1] neg_lo:[0,0,1] neg_hi:[0,0,0]
	v_pk_fma_f32 v[118:119], v[98:99], v[106:107], v[118:119] op_sel:[0,0,0] op_sel_hi:[0,1,1] neg_lo:[0,0,0] neg_hi:[0,1,0]
	v_pk_add_f32 v[92:93], v[84:85], v[112:113] neg_lo:[0,1] neg_hi:[0,1]
	v_pk_add_f32 v[94:95], v[86:87], v[114:115] neg_lo:[0,1] neg_hi:[0,1]
	v_pk_add_f32 v[96:97], v[88:89], v[116:117] neg_lo:[0,1] neg_hi:[0,1]
	v_pk_add_f32 v[98:99], v[90:91], v[118:119] neg_lo:[0,1] neg_hi:[0,1]
	v_pk_add_f32 v[84:85], v[84:85], v[112:113]
	v_pk_add_f32 v[86:87], v[86:87], v[114:115]
	v_pk_add_f32 v[88:89], v[88:89], v[116:117]
	v_pk_add_f32 v[90:91], v[90:91], v[118:119]
	ds_write2_b64 v130, v[84:85], v[86:87] offset1:17
	ds_write2_b64 v130, v[88:89], v[90:91] offset0:34 offset1:51
	ds_write2_b64 v130, v[92:93], v[94:95] offset0:68 offset1:85
	ds_write2_b64 v130, v[96:97], v[98:99] offset0:102 offset1:119
	s_waitcnt lgkmcnt(4)
; #define LAS __attribute__((address_space(3)))
; __device__ __forceinline__ cf twc(cf ws, int k16) { if (k16 == 0) return ws; if (k16 == 4) return cf{ws.y, -ws.x}; return cmul(ws, cf{c16(k16), -s16(k16)}); }
; template <int LR> __device__ __forceinline__ void dit_reg(cf (&x)[1 << LR], cf w) {
;     constexpr int R = 1 << LR; cf wsv[LR]; wsv[0] = w;
; #pragma unroll
;     for (int s = 1; s < LR; ++s) wsv[s] = cmul(wsv[s - 1], wsv[s - 1]);
; #pragma unroll
;     for (int s = LR - 1; s >= 0; --s) { const int half = R >> (s + 1);
; #pragma unroll
;         for (int m0 = 0; m0 < R; m0 += 2 * half)
; #pragma unroll
;             for (int mm = 0; mm < half; ++mm) { const int ia = m0 + mm, ib = ia + half; const cf a = x[ia];
;                 const cf b = cmulc(x[ib], twc(wsv[s], (mm << s) * (16 / R)));
;                 x[ia] = cf{a.x + b.x, a.y + b.y}; x[ib] = cf{a.x - b.x, a.y - b.y}; } }
; }
; __device__ __forceinline__ void lds_barrier() { asm volatile("s_waitcnt lgkmcnt(0)\n\ts_barrier" ::: "memory"); }
; template <int LR, bool INV> __device__ __forceinline__ void fft_pass(ldsf2 buf, int base, int stride, int twi) {
;     constexpr int R = 1 << LR; cf x[R];
;     const v2f wv = ((ldsf2)((LAS unsigned char*)buf + 139264))[twi];
; #pragma unroll
;     for (int m = 0; m < R; ++m) { const v2f v = buf[base + m * stride]; x[m] = cf{v.x, v.y}; }
;     const cf w{wv.x, wv.y};
;     if (INV) dit_reg<LR>(x, w); else dif_reg<LR>(x, w);
; #pragma unroll
;     for (int m = 0; m < R; ++m) buf[base + m * stride] = mkv2(x[m].x, x[m].y);
; }
; __device__ __forceinline__ void fft_inv_cba(ldsf2 buf) {
;     ...
;     for (int u = 0; u < 2; ++u) { const int j = l + 64 * u, o = j & 15, e0 = wv * 1024 + (j >> 4) * 128 + o; fft_pass<3, true>(buf, e0 + (e0 >> 4), 17, o * 64); }
	v_pk_mul_f32 v[164:165], v[142:143], v[110:111] op_sel:[1,1] op_sel_hi:[1,0]
	v_pk_mul_f32 v[166:167], v[154:155], v[110:111] op_sel:[1,1] op_sel_hi:[1,0]
	v_pk_mul_f32 v[168:169], v[158:159], v[110:111] op_sel:[1,1] op_sel_hi:[1,0]
	v_pk_mul_f32 v[170:171], v[162:163], v[110:111] op_sel:[1,1] op_sel_hi:[1,0]
	v_pk_fma_f32 v[164:165], v[142:143], v[110:111], v[164:165] op_sel:[0,0,0] op_sel_hi:[0,1,1] neg_lo:[0,0,0] neg_hi:[0,1,0]
	v_pk_fma_f32 v[166:167], v[154:155], v[110:111], v[166:167] op_sel:[0,0,0] op_sel_hi:[0,1,1] neg_lo:[0,0,0] neg_hi:[0,1,0]
	v_pk_fma_f32 v[168:169], v[158:159], v[110:111], v[168:169] op_sel:[0,0,0] op_sel_hi:[0,1,1] neg_lo:[0,0,0] neg_hi:[0,1,0]
	v_pk_fma_f32 v[170:171], v[162:163], v[110:111], v[170:171] op_sel:[0,0,0] op_sel_hi:[0,1,1] neg_lo:[0,0,0] neg_hi:[0,1,0]
	v_pk_add_f32 v[142:143], v[140:141], v[164:165] neg_lo:[0,1] neg_hi:[0,1]
	v_pk_add_f32 v[154:155], v[152:153], v[166:167] neg_lo:[0,1] neg_hi:[0,1]
	v_pk_add_f32 v[158:159], v[156:157], v[168:169] neg_lo:[0,1] neg_hi:[0,1]
	v_pk_add_f32 v[162:163], v[160:161], v[170:171] neg_lo:[0,1] neg_hi:[0,1]
	v_pk_add_f32 v[140:141], v[140:141], v[164:165]
	v_pk_add_f32 v[152:153], v[152:153], v[166:167]
	v_pk_add_f32 v[156:157], v[156:157], v[168:169]
	v_pk_add_f32 v[160:161], v[160:161], v[170:171]
	v_pk_mul_f32 v[164:165], v[152:153], v[108:109] op_sel:[1,1] op_sel_hi:[1,0]
	v_pk_mul_f32 v[166:167], v[154:155], v[108:109] op_sel:[1,0] op_sel_hi:[1,1]
	v_pk_mul_f32 v[168:169], v[160:161], v[108:109] op_sel:[1,1] op_sel_hi:[1,0]
	v_pk_mul_f32 v[170:171], v[162:163], v[108:109] op_sel:[1,0] op_sel_hi:[1,1]
	v_pk_fma_f32 v[164:165], v[152:153], v[108:109], v[164:165] op_sel:[0,0,0] op_sel_hi:[0,1,1] neg_lo:[0,0,0] neg_hi:[0,1,0]
	v_pk_fma_f32 v[166:167], v[154:155], v[108:109], v[166:167] op_sel:[0,1,0] op_sel_hi:[0,0,1] neg_lo:[0,0,1] neg_hi:[0,0,0]
	v_pk_fma_f32 v[168:169], v[160:161], v[108:109], v[168:169] op_sel:[0,0,0] op_sel_hi:[0,1,1] neg_lo:[0,0,0] neg_hi:[0,1,0]
	v_pk_fma_f32 v[170:171], v[162:163], v[108:109], v[170:171] op_sel:[0,1,0] op_sel_hi:[0,0,1] neg_lo:[0,0,1] neg_hi:[0,0,0]
	v_pk_add_f32 v[152:153], v[140:141], v[164:165] neg_lo:[0,1] neg_hi:[0,1]
	v_pk_add_f32 v[154:155], v[142:143], v[166:167] neg_lo:[0,1] neg_hi:[0,1]
	v_pk_add_f32 v[160:161], v[156:157], v[168:169] neg_lo:[0,1] neg_hi:[0,1]
	v_pk_add_f32 v[162:163], v[158:159], v[170:171] neg_lo:[0,1] neg_hi:[0,1]
	v_pk_add_f32 v[140:141], v[140:141], v[164:165]
	v_pk_add_f32 v[142:143], v[142:143], v[166:167]
	v_pk_add_f32 v[156:157], v[156:157], v[168:169]
	v_pk_add_f32 v[158:159], v[158:159], v[170:171]
	v_pk_mul_f32 v[164:165], v[156:157], v[100:101] op_sel:[1,1] op_sel_hi:[1,0]
	v_pk_mul_f32 v[166:167], v[158:159], v[104:105] op_sel:[1,1] op_sel_hi:[1,0]
	v_pk_mul_f32 v[168:169], v[160:161], v[100:101] op_sel:[1,0] op_sel_hi:[1,1]
	v_pk_mul_f32 v[170:171], v[162:163], v[106:107] op_sel:[1,1] op_sel_hi:[1,0]
	v_pk_fma_f32 v[164:165], v[156:157], v[100:101], v[164:165] op_sel:[0,0,0] op_sel_hi:[0,1,1] neg_lo:[0,0,0] neg_hi:[0,1,0]
	v_pk_fma_f32 v[166:167], v[158:159], v[104:105], v[166:167] op_sel:[0,0,0] op_sel_hi:[0,1,1] neg_lo:[0,0,0] neg_hi:[0,1,0]
	v_pk_fma_f32 v[168:169], v[160:161], v[100:101], v[168:169] op_sel:[0,1,0] op_sel_hi:[0,0,1] neg_lo:[0,0,1] neg_hi:[0,0,0]
	v_pk_fma_f32 v[170:171], v[162:163], v[106:107], v[170:171] op_sel:[0,0,0] op_sel_hi:[0,1,1] neg_lo:[0,0,0] neg_hi:[0,1,0]
	v_pk_add_f32 v[156:157], v[140:141], v[164:165] neg_lo:[0,1] neg_hi:[0,1]
	v_pk_add_f32 v[158:159], v[142:143], v[166:167] neg_lo:[0,1] neg_hi:[0,1]
	v_pk_add_f32 v[160:161], v[152:153], v[168:169] neg_lo:[0,1] neg_hi:[0,1]
	v_pk_add_f32 v[162:163], v[154:155], v[170:171] neg_lo:[0,1] neg_hi:[0,1]
	v_pk_add_f32 v[140:141], v[140:141], v[164:165]
	v_pk_add_f32 v[142:143], v[142:143], v[166:167]
	v_pk_add_f32 v[152:153], v[152:153], v[168:169]
	v_pk_add_f32 v[154:155], v[154:155], v[170:171]
	ds_write2_b64 v138, v[140:141], v[142:143] offset1:17
	ds_write2_b64 v138, v[152:153], v[154:155] offset0:34 offset1:51
	ds_write2_b64 v138, v[156:157], v[158:159] offset0:68 offset1:85
	ds_write2_b64 v138, v[160:161], v[162:163] offset0:102 offset1:119
	s_mov_b64 s[14:15], 0
	s_waitcnt lgkmcnt(0)
	s_mov_b32 s0, 0
	s_mov_b64 s[14:15], -1
